# in-proj epilogue: row-scale loads hoisted and q/kv sumsq atomics deferred; GLU epilogue: bias vectors loaded once, atomics deferred
# speedup vs baseline: 1.0103x; 1.0103x over previous
; DI float ss_get(const ssacc_t* p) { const ssacc_t v = *p; return (float)(unsigned)(v >> 32) + (float)(unsigned)(v & 0xffffffffull) * 2.3283064365386963e-10f; }
;     DI const bf16_t* KPE() const { return (const bf16_t*)(ws + WS_KPE); }
;     DI void operator()(const Acc& acc, const Unit& u, int wr, int wc, int fr, int fq) const {
;         const int pn = u.pn;
;         const ssacc_t* ssx = (const ssacc_t*)(ws + WS_SS) + (size_t)(SS_X + l) * M_; const float* rope = (const float*)(ws + WS_ROPE);
;         bf16_t *CQ = (bf16_t*)(ws + WS_CQ), *CKV = (bf16_t*)(ws + WS_CKV), *QD = (bf16_t*)(ws + WS_QD), *KD = (bf16_t*)(ws + WS_KD), *VD = (bf16_t*)(ws + WS_VD), *KPE = (bf16_t*)(ws + WS_KPE);
;         float* U = (float*)(ws + WS_U); ssacc_t *ssq = (ssacc_t*)(ws + WS_SS) + (size_t)(SS_Q + l) * M_, *sskv = (ssacc_t*)(ws + WS_SS) + (size_t)(SS_KV + l) * M_;
; #pragma unroll
;         for (int ai = 0; ai < 2; ++ai)
; #pragma unroll
;             for (int m = 0; m < 4; ++m) {
;                 asm volatile("" ::: "memory");
;                 const int row = u.pm * 256 + ai * 128 + wr * 64 + m * 16 + fr;
;                 const float rs = rsqrtf(ss_get(ssx + row) * (1.f / 2048.f) + EPS_);
;                 float sq = 0.f;
; #pragma unroll
;                 for (int bj = 0; bj < 2; ++bj) {
;                     f32x4 v0 = acc[ai][bj][m][0] * rs, v1 = acc[ai][bj][m][1] * rs;
;                     const int ct = bj * 128 + wc * 32 + 8 * fq;
;                     if (pn <= 1) { *(u32x4*)(CQ + (size_t)row * 512 + pn * 256 + ct) = pack8(v0, v1); sq += sq8(v0, v1); }
;                     else if (pn == 2) { *(u32x4*)(CKV + (size_t)row * 256 + ct) = pack8(v0, v1); sq += sq8(v0, v1); }
;                     else if (pn <= 4) { float* p = U + (size_t)row * 512 + (pn - 3) * 256 + ct; *(f32x4*)p = v0; *(f32x4*)(p + 4) = v1; }
;                     else if (pn <= 6) { v0 = v0 * QSCALE_DIL; v1 = v1 * QSCALE_DIL; *(u32x4*)(QD + (size_t)row * 512 + (pn - 5) * 256 + ct) = pack8(v0, v1); }
;                     else if (pn <= 8) { *(u32x4*)(KD + (size_t)row * 512 + (pn - 7) * 256 + ct) = pack8(v0, v1); }
;                     else if (pn <= 10) { *(u32x4*)(VD + (size_t)row * 512 + (pn - 9) * 256 + ct) = pack8(v0, v1); }
;                     else { if (ct < 64) { rope8(v0, v1, rope, row & 2047, ct >> 1); *(u32x4*)(KPE + (size_t)row * 64 + ct) = pack8(v0, v1); } }
.LBB0_197:
	v_lshl_add_u32 v152, s38, 8, v143
	v_ashrrev_i32_e32 v153, 31, v152
	v_lshl_add_u64 v[154:155], v[152:153], 3, s[62:63]
	global_load_dwordx2 v[212:213], v[154:155], off
	global_load_dwordx2 v[214:215], v[154:155], off offset:128
	global_load_dwordx2 v[216:217], v[154:155], off offset:256
	global_load_dwordx2 v[218:219], v[154:155], off offset:384
	global_load_dwordx2 v[220:221], v[154:155], off offset:1024
	global_load_dwordx2 v[222:223], v[154:155], off offset:1152
	global_load_dwordx2 v[224:225], v[154:155], off offset:1280
	global_load_dwordx2 v[226:227], v[154:155], off offset:1408
	s_cmp_gt_i32 s41, 1
	s_cselect_b64 s[14:15], -1, 0
	s_cmp_eq_u32 s41, 2
	s_cselect_b64 s[6:7], -1, 0
	s_cmp_lg_u32 s41, 2
	s_cselect_b64 s[16:17], -1, 0
	s_cmp_gt_u32 s41, 4
	s_cselect_b64 s[78:79], -1, 0
	s_cmp_gt_u32 s41, 6
	s_cselect_b64 s[76:77], -1, 0
	s_cmp_gt_u32 s41, 8
	s_cselect_b64 s[74:75], -1, 0
	s_cmp_lt_u32 s41, 11
	s_cselect_b64 s[72:73], -1, 0
	s_cmp_gt_u32 s41, 10
	s_cselect_b64 s[82:83], -1, 0
	s_lshl_b32 s38, s41, 8
	s_lshl_b64 s[18:19], s[38:39], 1
	s_add_u32 s84, s8, s18
	s_addc_u32 s85, s9, s19
	s_add_u32 s86, s84, s18
	s_addc_u32 s87, s85, s19
	s_ashr_i32 s19, s38, 31
	s_mov_b32 s18, s38
	s_lshl_b64 s[18:19], s[18:19], 1
	s_add_u32 s80, s64, s18
	s_addc_u32 s81, s65, s19
	s_min_u32 s40, s88, 32
	s_sub_i32 s38, 32, s40
	v_lshlrev_b64 v[168:169], 10, v[152:153]
	s_mov_b64 s[18:19], 0x1fafee00
	s_waitcnt vmcnt(7)
	v_mov_b32_e32 v136, v212
	v_mov_b32_e32 v137, v213
	v_mov_b32_e32 v128, v137
	v_lshlrev_b64 v[138:139], s40, v[128:129]
	v_min_u32_e32 v128, 1, v138
	v_or_b32_e32 v128, v139, v128
	v_cvt_f32_u32_e32 v128, v128
	v_cvt_f32_u32_e32 v136, v136
	v_ldexp_f32 v128, v128, s38
	v_fmac_f32_e32 v128, 0x2f800000, v136
	v_fmamk_f32 v128, v128, 0x3a000000, v195
	v_cmp_gt_f32_e32 vcc, s27, v128
	v_mul_f32_e32 v136, 0x4b800000, v128
	s_nop 0
	v_cndmask_b32_e32 v128, v128, v136, vcc
	v_rsq_f32_e32 v128, v128
	s_nop 0
	v_mul_f32_e32 v136, 0x45800000, v128
	v_cndmask_b32_e32 v166, v128, v136, vcc
	v_lshl_add_u64 v[136:137], s[84:85], 0, v[168:169]
	v_lshl_add_u64 v[164:165], v[136:137], 0, s[18:19]
	s_mov_b64 s[18:19], 0x1f2ff200
	v_lshl_add_u64 v[162:163], v[136:137], 0, s[18:19]
	s_mov_b64 s[18:19], 0x1eaff600
	v_lshl_add_u64 v[160:161], v[136:137], 0, s[18:19]
	v_lshlrev_b64 v[136:137], 11, v[152:153]
	v_lshl_add_u64 v[136:137], s[86:87], 0, v[136:137]
	s_mov_b64 s[18:19], 0x1daff400
	v_lshl_add_u64 v[158:159], v[136:137], 0, s[18:19]
	v_lshlrev_b64 v[136:137], 9, v[152:153]
	v_lshl_add_u64 v[156:157], s[66:67], 0, v[136:137]
	v_pk_mul_f32 v[138:139], v[122:123], v[166:167] op_sel_hi:[1,0]
	v_pk_mul_f32 v[136:137], v[120:121], v[166:167] op_sel_hi:[1,0]
	v_pk_mul_f32 v[122:123], v[126:127], v[166:167] op_sel_hi:[1,0]
	v_pk_mul_f32 v[120:121], v[124:125], v[166:167] op_sel_hi:[1,0]
	s_mov_b64 s[18:19], -1
	s_and_b64 vcc, exec, s[14:15]
	s_cbranch_vccz .LBB0_221
	s_and_b64 vcc, exec, s[16:17]
	s_cbranch_vccz .LBB0_218
	s_and_b64 vcc, exec, s[78:79]
	s_cbranch_vccz .LBB0_215
	s_and_b64 vcc, exec, s[76:77]
	s_cbranch_vccz .LBB0_212
	s_and_b64 vcc, exec, s[74:75]
	s_cbranch_vccz .LBB0_209
	s_and_b64 vcc, exec, s[82:83]
	s_cbranch_vccz .LBB0_206
	v_readlane_b32 s18, v255, 1
	v_readlane_b32 s19, v255, 2
	s_andn2_b64 vcc, exec, s[18:19]
	s_cbranch_vccnz .LBB0_205
	v_lshlrev_b32_e32 v124, 8, v152
	s_mov_b32 s4, 0x7cf00
	v_readlane_b32 s18, v255, 3
	v_and_or_b32 v128, v124, s4, v170
	v_readlane_b32 s19, v255, 4
	s_nop 4
	global_load_dwordx4 v[124:127], v128, s[18:19] offset:16
	global_load_dwordx4 v[172:175], v128, s[18:19]
	v_lshlrev_b64 v[176:177], 7, v[152:153]
	s_waitcnt vmcnt(0)
	v_pk_mul_f32 v[178:179], v[136:137], v[172:173] op_sel:[1,1] op_sel_hi:[0,1]
	v_mov_b32_e32 v128, v175
	v_pk_fma_f32 v[180:181], v[136:137], v[172:173], v[178:179] neg_lo:[0,0,1] neg_hi:[0,0,1]
	v_pk_fma_f32 v[172:173], v[136:137], v[172:173], v[178:179] op_sel_hi:[1,0,1]
	v_pk_mul_f32 v[178:179], v[138:139], v[128:129] op_sel:[1,0] op_sel_hi:[0,0]
	v_pk_fma_f32 v[182:183], v[138:139], v[174:175], v[178:179] neg_lo:[0,0,1] neg_hi:[0,0,1]
	v_pk_fma_f32 v[174:175], v[138:139], v[174:175], v[178:179] op_sel_hi:[1,0,1]
	v_pk_mul_f32 v[178:179], v[120:121], v[124:125] op_sel:[1,1] op_sel_hi:[0,1]
	v_pk_fma_f32 v[208:209], v[120:121], v[124:125], v[178:179] neg_lo:[0,0,1] neg_hi:[0,0,1]
	v_pk_fma_f32 v[178:179], v[120:121], v[124:125], v[178:179] op_sel_hi:[1,0,1]
	v_mov_b32_e32 v124, v127
	v_pk_mul_f32 v[124:125], v[122:123], v[124:125] op_sel:[1,0] op_sel_hi:[0,0]
	v_pk_fma_f32 v[210:211], v[122:123], v[126:127], v[124:125] neg_lo:[0,0,1] neg_hi:[0,0,1]
	v_pk_fma_f32 v[126:127], v[122:123], v[126:127], v[124:125] op_sel_hi:[1,0,1]
	v_cvt_pk_bf16_f32 v124, v180, v173
	v_cvt_pk_bf16_f32 v125, v182, v175
	v_cvt_pk_bf16_f32 v126, v208, v179
	v_cvt_pk_bf16_f32 v127, v210, v127
	v_lshl_add_u64 v[172:173], v[146:147], 0, v[176:177]
	global_store_dwordx4 v[172:173], v[124:127], off

; DI void ss_add(ssacc_t* p, float v) { atomicAdd(p, (ssacc_t)__float2ull_rn(v * 4294967296.f)); }
; DI float quad_sum(float s) { s += __shfl_xor(s, 16); s += __shfl_xor(s, 32); return s; }
;     DI void operator()(const Acc& acc, const Unit& u, int wr, int wc, int fr, int fq) const {
;     ...
;                 if (pn <= 2) { sq = quad_sum(sq); if (fq == 0) ss_add((pn <= 1 ? ssq : sskv) + row, sq); }
.LBB0_245:
	s_cmp_lt_i32 s41, 3
	s_cselect_b64 s[14:15], -1, 0
	s_and_b64 s[6:7], s[6:7], exec
	s_cselect_b32 s4, 9, 5
	s_add_i32 s4, s4, s54
	s_lshl_b32 s4, s4, 16
	s_add_u32 s88, s60, s4
	s_addc_u32 s89, s61, 0
	s_cmp_gt_i32 s41, 2
	s_cbranch_scc1 .LBB0_249
	v_and_b32_e32 v113, 64, v199
	v_xor_b32_e32 v112, 16, v199
	v_add_u32_e32 v113, 64, v113
	v_cmp_lt_i32_e32 vcc, v112, v113
	v_xor_b32_e32 v114, 32, v199
	s_nop 0
	v_cndmask_b32_e32 v112, v199, v112, vcc
	v_lshlrev_b32_e32 v112, 2, v112
	ds_bpermute_b32 v112, v112, v120
	v_cmp_lt_i32_e32 vcc, v114, v113
	s_waitcnt lgkmcnt(0)
	v_add_f32_e32 v112, v120, v112
	v_cndmask_b32_e32 v113, v199, v114, vcc
	v_lshlrev_b32_e32 v113, 2, v113
	ds_bpermute_b32 v113, v113, v112
	s_and_saveexec_b64 s[6:7], s[46:47]
	s_cbranch_execz .LBB0_248
	s_waitcnt lgkmcnt(0)
	v_add_f32_e32 v112, v112, v113
	v_mul_f32_e32 v112, 0x4f800000, v112
	v_rndne_f32_e32 v112, v112
	v_mul_f32_e32 v113, 0x2f800000, v112
	v_floor_f32_e32 v113, v113
	v_fmac_f32_e32 v112, 0xcf800000, v113
	v_cvt_u32_f32_e32 v112, v112
	v_cvt_u32_f32_e32 v113, v113
	v_mov_b32_e32 v228, v112
	v_mov_b32_e32 v229, v113

; DI float ss_get(const ssacc_t* p) { const ssacc_t v = *p; return (float)(unsigned)(v >> 32) + (float)(unsigned)(v & 0xffffffffull) * 2.3283064365386963e-10f; }
; DI float sq8(const f32x4& a, const f32x4& b) { return (a[0] * a[0] + a[1] * a[1]) + (a[2] * a[2] + a[3] * a[3]) + (b[0] * b[0] + b[1] * b[1]) + (b[2] * b[2] + b[3] * b[3]); }
; DI u32x4 pack8(const f32x4& a, const f32x4& b) { u32x4 w; w.x = cvtpk(a[0], a[1]); w.y = cvtpk(a[2], a[3]); w.z = cvtpk(b[0], b[1]); w.w = cvtpk(b[2], b[3]); return w; }
;     DI const bf16_t* KPE() const { return (const bf16_t*)(ws + WS_KPE); }
;     DI const bf16_t* QD() const { return (const bf16_t*)(ws + WS_QD); }
;     DI const bf16_t* KD() const { return (const bf16_t*)(ws + WS_KD); }
;     DI const bf16_t* VD() const { return (const bf16_t*)(ws + WS_VD); }
; #define U WSF(WS_U)
; #define U WSF(WS_U)
;     DI void operator()(const Acc& acc, const Unit& u, int wr, int wc, int fr, int fq) const {
;     ...
;             for (int m = 0; m < 4; ++m) {
;                 asm volatile("" ::: "memory");
;                 const int row = u.pm * 256 + ai * 128 + wr * 64 + m * 16 + fr;
;                 const float rs = rsqrtf(ss_get(ssx + row) * (1.f / 2048.f) + EPS_);
;                 float sq = 0.f;
; #pragma unroll
;                 for (int bj = 0; bj < 2; ++bj) {
;                     f32x4 v0 = acc[ai][bj][m][0] * rs, v1 = acc[ai][bj][m][1] * rs;
;                     const int ct = bj * 128 + wc * 32 + 8 * fq;
;                     if (pn <= 1) { *(u32x4*)(CQ + (size_t)row * 512 + pn * 256 + ct) = pack8(v0, v1); sq += sq8(v0, v1); }
;                     else if (pn == 2) { *(u32x4*)(CKV + (size_t)row * 256 + ct) = pack8(v0, v1); sq += sq8(v0, v1); }
;                     else if (pn <= 4) { float* p = U + (size_t)row * 512 + (pn - 3) * 256 + ct; *(f32x4*)p = v0; *(f32x4*)(p + 4) = v1; }
;                     else if (pn <= 6) { v0 = v0 * QSCALE_DIL; v1 = v1 * QSCALE_DIL; *(u32x4*)(QD + (size_t)row * 512 + (pn - 5) * 256 + ct) = pack8(v0, v1); }
;                     else if (pn <= 8) { *(u32x4*)(KD + (size_t)row * 512 + (pn - 7) * 256 + ct) = pack8(v0, v1); }
;                     else if (pn <= 10) { *(u32x4*)(VD + (size_t)row * 512 + (pn - 9) * 256 + ct) = pack8(v0, v1); }
;                     else { if (ct < 64) { rope8(v0, v1, rope, row & 2047, ct >> 1); *(u32x4*)(KPE + (size_t)row * 64 + ct) = pack8(v0, v1); } }
.LBB0_249:
	s_waitcnt lgkmcnt(0)
	v_or_b32_e32 v136, 16, v152
	v_ashrrev_i32_e32 v137, 31, v136
	v_lshlrev_b64 v[116:117], 9, v[136:137]
	v_lshlrev_b64 v[126:127], 10, v[136:137]
	v_lshl_add_u64 v[122:123], s[84:85], 0, v[126:127]
	s_mov_b64 s[6:7], 0x1fafee00
	v_lshl_add_u64 v[120:121], v[122:123], 0, s[6:7]
	s_mov_b64 s[16:17], 0x1f2ff200
	v_lshlrev_b64 v[114:115], 11, v[136:137]
	v_lshl_add_u64 v[114:115], s[86:87], 0, v[114:115]
	s_and_b64 vcc, exec, s[52:53]
	s_waitcnt vmcnt(6)
	v_mov_b32_e32 v112, v214
	v_mov_b32_e32 v113, v215
	v_mov_b32_e32 v128, v113
	v_lshlrev_b64 v[118:119], s40, v[128:129]
	v_min_u32_e32 v113, 1, v118
	v_or_b32_e32 v113, v119, v113
	v_cvt_f32_u32_e32 v118, v113
	v_cvt_f32_u32_e32 v119, v112
	v_lshl_add_u64 v[112:113], s[66:67], 0, v[116:117]
	v_ldexp_f32 v116, v118, s38
	v_fmac_f32_e32 v116, 0x2f800000, v119
	v_fmamk_f32 v116, v116, 0x3a000000, v195
	v_mul_f32_e32 v117, 0x4b800000, v116
	v_cmp_gt_f32_e64 s[6:7], s27, v116
	v_lshl_add_u64 v[118:119], v[122:123], 0, s[16:17]
	s_mov_b64 s[16:17], 0x1eaff600
	v_cndmask_b32_e64 v116, v116, v117, s[6:7]
	v_rsq_f32_e32 v125, v116
	v_lshl_add_u64 v[116:117], v[122:123], 0, s[16:17]
	s_mov_b64 s[16:17], 0x1daff400
	v_lshl_add_u64 v[114:115], v[114:115], 0, s[16:17]
	v_mul_f32_e32 v122, 0x45800000, v125
	v_cndmask_b32_e64 v122, v125, v122, s[6:7]
	v_pk_mul_f32 v[110:111], v[110:111], v[122:123] op_sel_hi:[1,0]
	v_pk_mul_f32 v[108:109], v[108:109], v[122:123] op_sel_hi:[1,0]
	v_pk_mul_f32 v[106:107], v[106:107], v[122:123] op_sel_hi:[1,0]
	v_pk_mul_f32 v[104:105], v[104:105], v[122:123] op_sel_hi:[1,0]
	s_mov_b64 s[6:7], -1
	s_cbranch_vccnz .LBB0_273
	s_and_b64 vcc, exec, s[50:51]
	s_cbranch_vccnz .LBB0_270
	s_andn2_b64 vcc, exec, s[78:79]
	s_cbranch_vccnz .LBB0_267
	s_andn2_b64 vcc, exec, s[76:77]
	s_cbranch_vccnz .LBB0_264
	s_andn2_b64 vcc, exec, s[74:75]
	s_cbranch_vccnz .LBB0_261
	s_andn2_b64 vcc, exec, s[82:83]
	s_cbranch_vccnz .LBB0_258
	v_readlane_b32 s6, v255, 1
	v_readlane_b32 s7, v255, 2
	s_andn2_b64 vcc, exec, s[6:7]
	s_cbranch_vccnz .LBB0_257
	v_lshlrev_b32_e32 v123, 8, v136
	s_mov_b32 s4, 0x7df00
	v_readlane_b32 s6, v255, 3
	v_and_or_b32 v123, v123, s4, v170
	v_readlane_b32 s7, v255, 4
	v_lshlrev_b64 v[160:161], 7, v[136:137]
	s_nop 3
	global_load_dwordx4 v[136:139], v123, s[6:7] offset:16
	global_load_dwordx4 v[156:159], v123, s[6:7]
	s_waitcnt vmcnt(0)
	v_pk_mul_f32 v[162:163], v[108:109], v[156:157] op_sel:[1,1] op_sel_hi:[0,1]
	v_mov_b32_e32 v128, v159
	v_pk_fma_f32 v[164:165], v[108:109], v[156:157], v[162:163] neg_lo:[0,0,1] neg_hi:[0,0,1]
	v_pk_fma_f32 v[156:157], v[108:109], v[156:157], v[162:163] op_sel_hi:[1,0,1]
	v_pk_mul_f32 v[162:163], v[110:111], v[128:129] op_sel:[1,0] op_sel_hi:[0,0]
	v_pk_fma_f32 v[166:167], v[110:111], v[158:159], v[162:163] neg_lo:[0,0,1] neg_hi:[0,0,1]
	v_pk_fma_f32 v[158:159], v[110:111], v[158:159], v[162:163] op_sel_hi:[1,0,1]
	v_pk_mul_f32 v[162:163], v[104:105], v[136:137] op_sel:[1,1] op_sel_hi:[0,1]
	v_mov_b32_e32 v128, v139
	v_pk_fma_f32 v[168:169], v[104:105], v[136:137], v[162:163] neg_lo:[0,0,1] neg_hi:[0,0,1]
	v_pk_fma_f32 v[162:163], v[104:105], v[136:137], v[162:163] op_sel_hi:[1,0,1]
	v_pk_mul_f32 v[136:137], v[106:107], v[128:129] op_sel:[1,0] op_sel_hi:[0,0]
	v_pk_fma_f32 v[172:173], v[106:107], v[138:139], v[136:137] neg_lo:[0,0,1] neg_hi:[0,0,1]
	v_pk_fma_f32 v[138:139], v[106:107], v[138:139], v[136:137] op_sel_hi:[1,0,1]
	v_cvt_pk_bf16_f32 v136, v164, v157
	v_cvt_pk_bf16_f32 v137, v166, v159
	v_cvt_pk_bf16_f32 v138, v168, v163
	v_cvt_pk_bf16_f32 v139, v172, v139
	v_lshl_add_u64 v[156:157], v[146:147], 0, v[160:161]
	global_store_dwordx4 v[156:157], v[136:139], off

; DI void ss_add(ssacc_t* p, float v) { atomicAdd(p, (ssacc_t)__float2ull_rn(v * 4294967296.f)); }
; DI float quad_sum(float s) { s += __shfl_xor(s, 16); s += __shfl_xor(s, 32); return s; }
;     DI void operator()(const Acc& acc, const Unit& u, int wr, int wc, int fr, int fq) const {
;     ...
;                 if (pn <= 2) { sq = quad_sum(sq); if (fq == 0) ss_add((pn <= 1 ? ssq : sskv) + row, sq); }
.LBB0_298:
	v_mbcnt_hi_u32_b32 v97, -1, v189
	v_and_b32_e32 v98, 64, v97
	v_xor_b32_e32 v96, 16, v97
	v_add_u32_e32 v98, 64, v98
	v_cmp_lt_i32_e32 vcc, v96, v98
	v_xor_b32_e32 v99, 32, v97
	s_nop 0
	v_cndmask_b32_e32 v96, v97, v96, vcc
	v_lshlrev_b32_e32 v96, 2, v96
	ds_bpermute_b32 v96, v96, v104
	v_cmp_lt_i32_e32 vcc, v99, v98
	s_waitcnt lgkmcnt(0)
	v_add_f32_e32 v96, v104, v96
	v_cndmask_b32_e32 v97, v97, v99, vcc
	v_lshlrev_b32_e32 v97, 2, v97
	ds_bpermute_b32 v97, v97, v96
	s_and_saveexec_b64 s[6:7], s[46:47]
	s_cbranch_execz .LBB0_300
	s_waitcnt lgkmcnt(0)
	v_add_f32_e32 v96, v96, v97
	v_mul_f32_e32 v96, 0x4f800000, v96
	v_rndne_f32_e32 v96, v96
	v_mul_f32_e32 v97, 0x2f800000, v96
	v_floor_f32_e32 v97, v97
	v_fmac_f32_e32 v96, 0xcf800000, v97
	v_cvt_u32_f32_e32 v96, v96
	v_cvt_u32_f32_e32 v97, v97
	v_mov_b32_e32 v230, v96
	v_mov_b32_e32 v231, v97

; DI float ss_get(const ssacc_t* p) { const ssacc_t v = *p; return (float)(unsigned)(v >> 32) + (float)(unsigned)(v & 0xffffffffull) * 2.3283064365386963e-10f; }
; DI float sq8(const f32x4& a, const f32x4& b) { return (a[0] * a[0] + a[1] * a[1]) + (a[2] * a[2] + a[3] * a[3]) + (b[0] * b[0] + b[1] * b[1]) + (b[2] * b[2] + b[3] * b[3]); }
; DI u32x4 pack8(const f32x4& a, const f32x4& b) { u32x4 w; w.x = cvtpk(a[0], a[1]); w.y = cvtpk(a[2], a[3]); w.z = cvtpk(b[0], b[1]); w.w = cvtpk(b[2], b[3]); return w; }
;     DI const bf16_t* KPE() const { return (const bf16_t*)(ws + WS_KPE); }
;     DI const bf16_t* QD() const { return (const bf16_t*)(ws + WS_QD); }
;     DI const bf16_t* KD() const { return (const bf16_t*)(ws + WS_KD); }
;     DI const bf16_t* VD() const { return (const bf16_t*)(ws + WS_VD); }
; #define U WSF(WS_U)
; #define U WSF(WS_U)
;     DI void operator()(const Acc& acc, const Unit& u, int wr, int wc, int fr, int fq) const {
;     ...
;             for (int m = 0; m < 4; ++m) {
;                 asm volatile("" ::: "memory");
;                 const int row = u.pm * 256 + ai * 128 + wr * 64 + m * 16 + fr;
;                 const float rs = rsqrtf(ss_get(ssx + row) * (1.f / 2048.f) + EPS_);
;                 float sq = 0.f;
; #pragma unroll
;                 for (int bj = 0; bj < 2; ++bj) {
;                     f32x4 v0 = acc[ai][bj][m][0] * rs, v1 = acc[ai][bj][m][1] * rs;
;                     const int ct = bj * 128 + wc * 32 + 8 * fq;
;                     if (pn <= 1) { *(u32x4*)(CQ + (size_t)row * 512 + pn * 256 + ct) = pack8(v0, v1); sq += sq8(v0, v1); }
;                     else if (pn == 2) { *(u32x4*)(CKV + (size_t)row * 256 + ct) = pack8(v0, v1); sq += sq8(v0, v1); }
;                     else if (pn <= 4) { float* p = U + (size_t)row * 512 + (pn - 3) * 256 + ct; *(f32x4*)p = v0; *(f32x4*)(p + 4) = v1; }
;                     else if (pn <= 6) { v0 = v0 * QSCALE_DIL; v1 = v1 * QSCALE_DIL; *(u32x4*)(QD + (size_t)row * 512 + (pn - 5) * 256 + ct) = pack8(v0, v1); }
;                     else if (pn <= 8) { *(u32x4*)(KD + (size_t)row * 512 + (pn - 7) * 256 + ct) = pack8(v0, v1); }
;                     else if (pn <= 10) { *(u32x4*)(VD + (size_t)row * 512 + (pn - 9) * 256 + ct) = pack8(v0, v1); }
;                     else { if (ct < 64) { rope8(v0, v1, rope, row & 2047, ct >> 1); *(u32x4*)(KPE + (size_t)row * 64 + ct) = pack8(v0, v1); } }
.LBB0_301:
	s_waitcnt lgkmcnt(0)
	v_or_b32_e32 v110, 32, v152
	v_ashrrev_i32_e32 v111, 31, v110
	v_lshlrev_b64 v[100:101], 9, v[110:111]
	v_lshlrev_b64 v[108:109], 10, v[110:111]
	v_lshl_add_u64 v[106:107], s[84:85], 0, v[108:109]
	s_mov_b64 s[6:7], 0x1fafee00
	v_lshl_add_u64 v[104:105], v[106:107], 0, s[6:7]
	s_mov_b64 s[14:15], 0x1f2ff200
	v_lshlrev_b64 v[98:99], 11, v[110:111]
	v_lshl_add_u64 v[98:99], s[86:87], 0, v[98:99]
	s_and_b64 vcc, exec, s[52:53]
	s_waitcnt vmcnt(5)
	v_mov_b32_e32 v96, v216
	v_mov_b32_e32 v97, v217
	v_mov_b32_e32 v128, v97
	v_lshlrev_b64 v[102:103], s40, v[128:129]
	v_min_u32_e32 v97, 1, v102
	v_or_b32_e32 v97, v103, v97
	v_cvt_f32_u32_e32 v102, v97
	v_cvt_f32_u32_e32 v103, v96
	v_lshl_add_u64 v[96:97], s[66:67], 0, v[100:101]
	v_ldexp_f32 v100, v102, s38
	v_fmac_f32_e32 v100, 0x2f800000, v103
	v_fmamk_f32 v100, v100, 0x3a000000, v195
	v_mul_f32_e32 v101, 0x4b800000, v100
	v_cmp_gt_f32_e64 s[6:7], s27, v100
	v_lshl_add_u64 v[102:103], v[106:107], 0, s[14:15]
	s_mov_b64 s[14:15], 0x1eaff600
	v_cndmask_b32_e64 v100, v100, v101, s[6:7]
	v_rsq_f32_e32 v112, v100
	v_lshl_add_u64 v[100:101], v[106:107], 0, s[14:15]
	s_mov_b64 s[14:15], 0x1daff400
	v_lshl_add_u64 v[98:99], v[98:99], 0, s[14:15]
	v_mul_f32_e32 v106, 0x45800000, v112
	v_cndmask_b32_e64 v106, v112, v106, s[6:7]
	v_pk_mul_f32 v[94:95], v[94:95], v[106:107] op_sel_hi:[1,0]
	v_pk_mul_f32 v[92:93], v[92:93], v[106:107] op_sel_hi:[1,0]
	v_pk_mul_f32 v[90:91], v[90:91], v[106:107] op_sel_hi:[1,0]
	v_pk_mul_f32 v[88:89], v[88:89], v[106:107] op_sel_hi:[1,0]
	s_mov_b64 s[6:7], -1
	s_cbranch_vccnz .LBB0_325
	s_and_b64 vcc, exec, s[50:51]
	s_cbranch_vccnz .LBB0_322
	s_andn2_b64 vcc, exec, s[78:79]
	s_cbranch_vccnz .LBB0_319
	s_andn2_b64 vcc, exec, s[76:77]
	s_cbranch_vccnz .LBB0_316
	s_andn2_b64 vcc, exec, s[74:75]
	s_cbranch_vccnz .LBB0_313
	s_andn2_b64 vcc, exec, s[82:83]
	s_cbranch_vccnz .LBB0_310
	v_readlane_b32 s6, v255, 1
	v_readlane_b32 s7, v255, 2
	s_andn2_b64 vcc, exec, s[6:7]
	s_cbranch_vccnz .LBB0_309
	v_lshlrev_b32_e32 v107, 8, v110
	s_mov_b32 s4, 0x7ef00
	v_readlane_b32 s6, v255, 3
	v_and_or_b32 v107, v107, s4, v170
	v_readlane_b32 s7, v255, 4
	v_lshlrev_b64 v[118:119], 7, v[110:111]
	s_nop 3
	global_load_dwordx4 v[110:113], v107, s[6:7] offset:16
	global_load_dwordx4 v[114:117], v107, s[6:7]
	s_waitcnt vmcnt(0)
	v_pk_mul_f32 v[120:121], v[92:93], v[114:115] op_sel:[1,1] op_sel_hi:[0,1]
	v_pk_fma_f32 v[122:123], v[92:93], v[114:115], v[120:121] neg_lo:[0,0,1] neg_hi:[0,0,1]
	v_pk_fma_f32 v[114:115], v[92:93], v[114:115], v[120:121] op_sel_hi:[1,0,1]
	s_nop 0
	v_mov_b32_e32 v114, v117
	v_pk_mul_f32 v[120:121], v[94:95], v[114:115] op_sel:[1,0] op_sel_hi:[0,0]
	v_pk_fma_f32 v[126:127], v[94:95], v[116:117], v[120:121] neg_lo:[0,0,1] neg_hi:[0,0,1]
	v_pk_fma_f32 v[116:117], v[94:95], v[116:117], v[120:121] op_sel_hi:[1,0,1]
	v_pk_mul_f32 v[120:121], v[88:89], v[110:111] op_sel:[1,1] op_sel_hi:[0,1]
	v_pk_fma_f32 v[136:137], v[88:89], v[110:111], v[120:121] neg_lo:[0,0,1] neg_hi:[0,0,1]
	v_pk_fma_f32 v[120:121], v[88:89], v[110:111], v[120:121] op_sel_hi:[1,0,1]
	v_mov_b32_e32 v110, v113
	v_pk_mul_f32 v[110:111], v[90:91], v[110:111] op_sel:[1,0] op_sel_hi:[0,0]
	v_pk_fma_f32 v[138:139], v[90:91], v[112:113], v[110:111] neg_lo:[0,0,1] neg_hi:[0,0,1]
	v_pk_fma_f32 v[112:113], v[90:91], v[112:113], v[110:111] op_sel_hi:[1,0,1]
	v_cvt_pk_bf16_f32 v110, v122, v115
	v_cvt_pk_bf16_f32 v111, v126, v117
	v_cvt_pk_bf16_f32 v112, v136, v121
	v_cvt_pk_bf16_f32 v113, v138, v113
	v_lshl_add_u64 v[114:115], v[146:147], 0, v[118:119]
	global_store_dwordx4 v[114:115], v[110:113], off

; DI void ss_add(ssacc_t* p, float v) { atomicAdd(p, (ssacc_t)__float2ull_rn(v * 4294967296.f)); }
; DI float quad_sum(float s) { s += __shfl_xor(s, 16); s += __shfl_xor(s, 32); return s; }
;     DI void operator()(const Acc& acc, const Unit& u, int wr, int wc, int fr, int fq) const {
;     ...
;                 if (pn <= 2) { sq = quad_sum(sq); if (fq == 0) ss_add((pn <= 1 ? ssq : sskv) + row, sq); }
.LBB0_350:
	v_mbcnt_hi_u32_b32 v81, -1, v189
	v_and_b32_e32 v82, 64, v81
	v_xor_b32_e32 v80, 16, v81
	v_add_u32_e32 v82, 64, v82
	v_cmp_lt_i32_e32 vcc, v80, v82
	v_xor_b32_e32 v83, 32, v81
	s_nop 0
	v_cndmask_b32_e32 v80, v81, v80, vcc
	v_lshlrev_b32_e32 v80, 2, v80
	ds_bpermute_b32 v80, v80, v88
	v_cmp_lt_i32_e32 vcc, v83, v82
	s_waitcnt lgkmcnt(0)
	v_add_f32_e32 v80, v88, v80
	v_cndmask_b32_e32 v81, v81, v83, vcc
	v_lshlrev_b32_e32 v81, 2, v81
	ds_bpermute_b32 v81, v81, v80
	s_and_saveexec_b64 s[6:7], s[46:47]
	s_cbranch_execz .LBB0_352
	s_waitcnt lgkmcnt(0)
	v_add_f32_e32 v80, v80, v81
	v_mul_f32_e32 v80, 0x4f800000, v80
	v_rndne_f32_e32 v80, v80
	v_mul_f32_e32 v81, 0x2f800000, v80
	v_floor_f32_e32 v81, v81
	v_fmac_f32_e32 v80, 0xcf800000, v81
	v_cvt_u32_f32_e32 v80, v80
	v_cvt_u32_f32_e32 v81, v81
	v_mov_b32_e32 v232, v80
	v_mov_b32_e32 v233, v81

; DI float ss_get(const ssacc_t* p) { const ssacc_t v = *p; return (float)(unsigned)(v >> 32) + (float)(unsigned)(v & 0xffffffffull) * 2.3283064365386963e-10f; }
; DI float sq8(const f32x4& a, const f32x4& b) { return (a[0] * a[0] + a[1] * a[1]) + (a[2] * a[2] + a[3] * a[3]) + (b[0] * b[0] + b[1] * b[1]) + (b[2] * b[2] + b[3] * b[3]); }
; DI u32x4 pack8(const f32x4& a, const f32x4& b) { u32x4 w; w.x = cvtpk(a[0], a[1]); w.y = cvtpk(a[2], a[3]); w.z = cvtpk(b[0], b[1]); w.w = cvtpk(b[2], b[3]); return w; }
;     DI const bf16_t* KPE() const { return (const bf16_t*)(ws + WS_KPE); }
;     DI const bf16_t* QD() const { return (const bf16_t*)(ws + WS_QD); }
;     DI const bf16_t* KD() const { return (const bf16_t*)(ws + WS_KD); }
;     DI const bf16_t* VD() const { return (const bf16_t*)(ws + WS_VD); }
; #define U WSF(WS_U)
; #define U WSF(WS_U)
;     DI void operator()(const Acc& acc, const Unit& u, int wr, int wc, int fr, int fq) const {
;     ...
;             for (int m = 0; m < 4; ++m) {
;                 asm volatile("" ::: "memory");
;                 const int row = u.pm * 256 + ai * 128 + wr * 64 + m * 16 + fr;
;                 const float rs = rsqrtf(ss_get(ssx + row) * (1.f / 2048.f) + EPS_);
;                 float sq = 0.f;
; #pragma unroll
;                 for (int bj = 0; bj < 2; ++bj) {
;                     f32x4 v0 = acc[ai][bj][m][0] * rs, v1 = acc[ai][bj][m][1] * rs;
;                     const int ct = bj * 128 + wc * 32 + 8 * fq;
;                     if (pn <= 1) { *(u32x4*)(CQ + (size_t)row * 512 + pn * 256 + ct) = pack8(v0, v1); sq += sq8(v0, v1); }
;                     else if (pn == 2) { *(u32x4*)(CKV + (size_t)row * 256 + ct) = pack8(v0, v1); sq += sq8(v0, v1); }
;                     else if (pn <= 4) { float* p = U + (size_t)row * 512 + (pn - 3) * 256 + ct; *(f32x4*)p = v0; *(f32x4*)(p + 4) = v1; }
;                     else if (pn <= 6) { v0 = v0 * QSCALE_DIL; v1 = v1 * QSCALE_DIL; *(u32x4*)(QD + (size_t)row * 512 + (pn - 5) * 256 + ct) = pack8(v0, v1); }
;                     else if (pn <= 8) { *(u32x4*)(KD + (size_t)row * 512 + (pn - 7) * 256 + ct) = pack8(v0, v1); }
;                     else if (pn <= 10) { *(u32x4*)(VD + (size_t)row * 512 + (pn - 9) * 256 + ct) = pack8(v0, v1); }
;                     else { if (ct < 64) { rope8(v0, v1, rope, row & 2047, ct >> 1); *(u32x4*)(KPE + (size_t)row * 64 + ct) = pack8(v0, v1); } }
.LBB0_353:
	s_waitcnt lgkmcnt(0)
	v_or_b32_e32 v94, 48, v152
	v_ashrrev_i32_e32 v95, 31, v94
	v_lshlrev_b64 v[84:85], 9, v[94:95]
	v_lshlrev_b64 v[92:93], 10, v[94:95]
	v_lshl_add_u64 v[90:91], s[84:85], 0, v[92:93]
	s_mov_b64 s[6:7], 0x1fafee00
	v_lshl_add_u64 v[88:89], v[90:91], 0, s[6:7]
	s_mov_b64 s[14:15], 0x1f2ff200
	v_lshlrev_b64 v[82:83], 11, v[94:95]
	v_lshl_add_u64 v[82:83], s[86:87], 0, v[82:83]
	s_and_b64 vcc, exec, s[52:53]
	s_waitcnt vmcnt(4)
	v_mov_b32_e32 v80, v218
	v_mov_b32_e32 v81, v219
	v_mov_b32_e32 v128, v81
	v_lshlrev_b64 v[86:87], s40, v[128:129]
	v_min_u32_e32 v81, 1, v86
	v_or_b32_e32 v81, v87, v81
	v_cvt_f32_u32_e32 v86, v81
	v_cvt_f32_u32_e32 v87, v80
	v_lshl_add_u64 v[80:81], s[66:67], 0, v[84:85]
	v_ldexp_f32 v84, v86, s38
	v_fmac_f32_e32 v84, 0x2f800000, v87
	v_fmamk_f32 v84, v84, 0x3a000000, v195
	v_mul_f32_e32 v85, 0x4b800000, v84
	v_cmp_gt_f32_e64 s[6:7], s27, v84
	v_lshl_add_u64 v[86:87], v[90:91], 0, s[14:15]
	s_mov_b64 s[14:15], 0x1eaff600
	v_cndmask_b32_e64 v84, v84, v85, s[6:7]
	v_rsq_f32_e32 v96, v84
	v_lshl_add_u64 v[84:85], v[90:91], 0, s[14:15]
	s_mov_b64 s[14:15], 0x1daff400
	v_lshl_add_u64 v[82:83], v[82:83], 0, s[14:15]
	v_mul_f32_e32 v90, 0x45800000, v96
	v_cndmask_b32_e64 v90, v96, v90, s[6:7]
	v_pk_mul_f32 v[78:79], v[78:79], v[90:91] op_sel_hi:[1,0]
	v_pk_mul_f32 v[76:77], v[76:77], v[90:91] op_sel_hi:[1,0]
	v_pk_mul_f32 v[74:75], v[74:75], v[90:91] op_sel_hi:[1,0]
	v_pk_mul_f32 v[72:73], v[72:73], v[90:91] op_sel_hi:[1,0]
	s_mov_b64 s[6:7], -1
	s_cbranch_vccnz .LBB0_377
	s_and_b64 vcc, exec, s[50:51]
	s_cbranch_vccnz .LBB0_374
	s_andn2_b64 vcc, exec, s[78:79]
	s_cbranch_vccnz .LBB0_371
	s_andn2_b64 vcc, exec, s[76:77]
	s_cbranch_vccnz .LBB0_368
	s_andn2_b64 vcc, exec, s[74:75]
	s_cbranch_vccnz .LBB0_365
	s_andn2_b64 vcc, exec, s[82:83]
	s_cbranch_vccnz .LBB0_362
	v_readlane_b32 s6, v255, 1
	v_readlane_b32 s7, v255, 2
	s_andn2_b64 vcc, exec, s[6:7]
	s_cbranch_vccnz .LBB0_361
	v_lshlrev_b32_e32 v91, 8, v94
	s_mov_b32 s4, 0x7ff00
	v_readlane_b32 s6, v255, 3
	v_and_or_b32 v91, v91, s4, v170
	v_readlane_b32 s7, v255, 4
	v_lshlrev_b64 v[102:103], 7, v[94:95]
	s_nop 3
	global_load_dwordx4 v[94:97], v91, s[6:7] offset:16
	global_load_dwordx4 v[98:101], v91, s[6:7]
	s_waitcnt vmcnt(0)
	v_pk_mul_f32 v[104:105], v[76:77], v[98:99] op_sel:[1,1] op_sel_hi:[0,1]
	v_pk_fma_f32 v[106:107], v[76:77], v[98:99], v[104:105] neg_lo:[0,0,1] neg_hi:[0,0,1]
	v_pk_fma_f32 v[98:99], v[76:77], v[98:99], v[104:105] op_sel_hi:[1,0,1]
	s_nop 0
	v_mov_b32_e32 v98, v101
	v_pk_mul_f32 v[104:105], v[78:79], v[98:99] op_sel:[1,0] op_sel_hi:[0,0]
	v_pk_fma_f32 v[108:109], v[78:79], v[100:101], v[104:105] neg_lo:[0,0,1] neg_hi:[0,0,1]
	v_pk_fma_f32 v[100:101], v[78:79], v[100:101], v[104:105] op_sel_hi:[1,0,1]
	v_pk_mul_f32 v[104:105], v[72:73], v[94:95] op_sel:[1,1] op_sel_hi:[0,1]
	v_pk_fma_f32 v[110:111], v[72:73], v[94:95], v[104:105] neg_lo:[0,0,1] neg_hi:[0,0,1]
	v_pk_fma_f32 v[104:105], v[72:73], v[94:95], v[104:105] op_sel_hi:[1,0,1]
	v_mov_b32_e32 v94, v97
	v_pk_mul_f32 v[94:95], v[74:75], v[94:95] op_sel:[1,0] op_sel_hi:[0,0]
	v_pk_fma_f32 v[112:113], v[74:75], v[96:97], v[94:95] neg_lo:[0,0,1] neg_hi:[0,0,1]
	v_pk_fma_f32 v[96:97], v[74:75], v[96:97], v[94:95] op_sel_hi:[1,0,1]
	v_cvt_pk_bf16_f32 v94, v106, v99
	v_cvt_pk_bf16_f32 v95, v108, v101
	v_cvt_pk_bf16_f32 v96, v110, v105
	v_cvt_pk_bf16_f32 v97, v112, v97
	v_lshl_add_u64 v[98:99], v[146:147], 0, v[102:103]
	global_store_dwordx4 v[98:99], v[94:97], off

; DI void ss_add(ssacc_t* p, float v) { atomicAdd(p, (ssacc_t)__float2ull_rn(v * 4294967296.f)); }
; DI float quad_sum(float s) { s += __shfl_xor(s, 16); s += __shfl_xor(s, 32); return s; }
;     DI void operator()(const Acc& acc, const Unit& u, int wr, int wc, int fr, int fq) const {
;     ...
;                 if (pn <= 2) { sq = quad_sum(sq); if (fq == 0) ss_add((pn <= 1 ? ssq : sskv) + row, sq); }
.LBB0_402:
	v_mbcnt_hi_u32_b32 v65, -1, v189
	v_and_b32_e32 v66, 64, v65
	v_xor_b32_e32 v64, 16, v65
	v_add_u32_e32 v66, 64, v66
	v_cmp_lt_i32_e32 vcc, v64, v66
	v_xor_b32_e32 v67, 32, v65
	s_nop 0
	v_cndmask_b32_e32 v64, v65, v64, vcc
	v_lshlrev_b32_e32 v64, 2, v64
	ds_bpermute_b32 v64, v64, v72
	v_cmp_lt_i32_e32 vcc, v67, v66
	s_waitcnt lgkmcnt(0)
	v_add_f32_e32 v64, v72, v64
	v_cndmask_b32_e32 v65, v65, v67, vcc
	v_lshlrev_b32_e32 v65, 2, v65
	ds_bpermute_b32 v65, v65, v64
	s_and_saveexec_b64 s[6:7], s[46:47]
	s_cbranch_execz .LBB0_404
	s_waitcnt lgkmcnt(0)
	v_add_f32_e32 v64, v64, v65
	v_mul_f32_e32 v64, 0x4f800000, v64
	v_rndne_f32_e32 v64, v64
	v_mul_f32_e32 v65, 0x2f800000, v64
	v_floor_f32_e32 v65, v65
	v_fmac_f32_e32 v64, 0xcf800000, v65
	v_cvt_u32_f32_e32 v64, v64
	v_cvt_u32_f32_e32 v65, v65
	v_mov_b32_e32 v234, v64
	v_mov_b32_e32 v235, v65

; DI float ss_get(const ssacc_t* p) { const ssacc_t v = *p; return (float)(unsigned)(v >> 32) + (float)(unsigned)(v & 0xffffffffull) * 2.3283064365386963e-10f; }
; DI float sq8(const f32x4& a, const f32x4& b) { return (a[0] * a[0] + a[1] * a[1]) + (a[2] * a[2] + a[3] * a[3]) + (b[0] * b[0] + b[1] * b[1]) + (b[2] * b[2] + b[3] * b[3]); }
; DI u32x4 pack8(const f32x4& a, const f32x4& b) { u32x4 w; w.x = cvtpk(a[0], a[1]); w.y = cvtpk(a[2], a[3]); w.z = cvtpk(b[0], b[1]); w.w = cvtpk(b[2], b[3]); return w; }
;     DI const bf16_t* KPE() const { return (const bf16_t*)(ws + WS_KPE); }
;     DI const bf16_t* QD() const { return (const bf16_t*)(ws + WS_QD); }
;     DI const bf16_t* KD() const { return (const bf16_t*)(ws + WS_KD); }
;     DI const bf16_t* VD() const { return (const bf16_t*)(ws + WS_VD); }
; #define U WSF(WS_U)
; #define U WSF(WS_U)
;     DI void operator()(const Acc& acc, const Unit& u, int wr, int wc, int fr, int fq) const {
;     ...
;             for (int m = 0; m < 4; ++m) {
;                 asm volatile("" ::: "memory");
;                 const int row = u.pm * 256 + ai * 128 + wr * 64 + m * 16 + fr;
;                 const float rs = rsqrtf(ss_get(ssx + row) * (1.f / 2048.f) + EPS_);
;                 float sq = 0.f;
; #pragma unroll
;                 for (int bj = 0; bj < 2; ++bj) {
;                     f32x4 v0 = acc[ai][bj][m][0] * rs, v1 = acc[ai][bj][m][1] * rs;
;                     const int ct = bj * 128 + wc * 32 + 8 * fq;
;                     if (pn <= 1) { *(u32x4*)(CQ + (size_t)row * 512 + pn * 256 + ct) = pack8(v0, v1); sq += sq8(v0, v1); }
;                     else if (pn == 2) { *(u32x4*)(CKV + (size_t)row * 256 + ct) = pack8(v0, v1); sq += sq8(v0, v1); }
;                     else if (pn <= 4) { float* p = U + (size_t)row * 512 + (pn - 3) * 256 + ct; *(f32x4*)p = v0; *(f32x4*)(p + 4) = v1; }
;                     else if (pn <= 6) { v0 = v0 * QSCALE_DIL; v1 = v1 * QSCALE_DIL; *(u32x4*)(QD + (size_t)row * 512 + (pn - 5) * 256 + ct) = pack8(v0, v1); }
;                     else if (pn <= 8) { *(u32x4*)(KD + (size_t)row * 512 + (pn - 7) * 256 + ct) = pack8(v0, v1); }
;                     else if (pn <= 10) { *(u32x4*)(VD + (size_t)row * 512 + (pn - 9) * 256 + ct) = pack8(v0, v1); }
;                     else { if (ct < 64) { rope8(v0, v1, rope, row & 2047, ct >> 1); *(u32x4*)(KPE + (size_t)row * 64 + ct) = pack8(v0, v1); } }
.LBB0_405:
	s_waitcnt lgkmcnt(0)
	v_add_u32_e32 v78, 0x80, v152
	v_ashrrev_i32_e32 v79, 31, v78
	v_lshlrev_b64 v[68:69], 9, v[78:79]
	v_lshlrev_b64 v[76:77], 10, v[78:79]
	v_lshl_add_u64 v[74:75], s[84:85], 0, v[76:77]
	s_mov_b64 s[6:7], 0x1fafee00
	v_lshl_add_u64 v[72:73], v[74:75], 0, s[6:7]
	s_mov_b64 s[14:15], 0x1f2ff200
	v_lshlrev_b64 v[66:67], 11, v[78:79]
	v_lshl_add_u64 v[66:67], s[86:87], 0, v[66:67]
	s_and_b64 vcc, exec, s[52:53]
	s_waitcnt vmcnt(3)
	v_mov_b32_e32 v64, v220
	v_mov_b32_e32 v65, v221
	v_mov_b32_e32 v128, v65
	v_lshlrev_b64 v[70:71], s40, v[128:129]
	v_min_u32_e32 v65, 1, v70
	v_or_b32_e32 v65, v71, v65
	v_cvt_f32_u32_e32 v70, v65
	v_cvt_f32_u32_e32 v71, v64
	v_lshl_add_u64 v[64:65], s[66:67], 0, v[68:69]
	v_ldexp_f32 v68, v70, s38
	v_fmac_f32_e32 v68, 0x2f800000, v71
	v_fmamk_f32 v68, v68, 0x3a000000, v195
	v_mul_f32_e32 v69, 0x4b800000, v68
	v_cmp_gt_f32_e64 s[6:7], s27, v68
	v_lshl_add_u64 v[70:71], v[74:75], 0, s[14:15]
	s_mov_b64 s[14:15], 0x1eaff600
	v_cndmask_b32_e64 v68, v68, v69, s[6:7]
	v_rsq_f32_e32 v80, v68
	v_lshl_add_u64 v[68:69], v[74:75], 0, s[14:15]
	s_mov_b64 s[14:15], 0x1daff400
	v_lshl_add_u64 v[66:67], v[66:67], 0, s[14:15]
	v_mul_f32_e32 v74, 0x45800000, v80
	v_cndmask_b32_e64 v74, v80, v74, s[6:7]
	v_pk_mul_f32 v[62:63], v[62:63], v[74:75] op_sel_hi:[1,0]
	v_pk_mul_f32 v[60:61], v[60:61], v[74:75] op_sel_hi:[1,0]
	v_pk_mul_f32 v[58:59], v[58:59], v[74:75] op_sel_hi:[1,0]
	v_pk_mul_f32 v[56:57], v[56:57], v[74:75] op_sel_hi:[1,0]
	s_mov_b64 s[6:7], -1
	s_cbranch_vccnz .LBB0_429
	s_and_b64 vcc, exec, s[50:51]
	s_cbranch_vccnz .LBB0_426
	s_andn2_b64 vcc, exec, s[78:79]
	s_cbranch_vccnz .LBB0_423
	s_andn2_b64 vcc, exec, s[76:77]
	s_cbranch_vccnz .LBB0_420
	s_andn2_b64 vcc, exec, s[74:75]
	s_cbranch_vccnz .LBB0_417
	s_andn2_b64 vcc, exec, s[82:83]
	s_cbranch_vccnz .LBB0_414
	v_readlane_b32 s6, v255, 1
	v_readlane_b32 s7, v255, 2
	s_andn2_b64 vcc, exec, s[6:7]
	s_cbranch_vccnz .LBB0_413
	v_lshlrev_b32_e32 v75, 8, v78
	s_mov_b32 s4, 0x7cf00
	v_readlane_b32 s6, v255, 3
	v_and_or_b32 v75, v75, s4, v170
	v_readlane_b32 s7, v255, 4
	v_lshlrev_b64 v[86:87], 7, v[78:79]
	s_nop 3
	global_load_dwordx4 v[78:81], v75, s[6:7] offset:16
	global_load_dwordx4 v[82:85], v75, s[6:7]
	s_waitcnt vmcnt(0)
	v_pk_mul_f32 v[88:89], v[60:61], v[82:83] op_sel:[1,1] op_sel_hi:[0,1]
	v_pk_fma_f32 v[90:91], v[60:61], v[82:83], v[88:89] neg_lo:[0,0,1] neg_hi:[0,0,1]
	v_pk_fma_f32 v[82:83], v[60:61], v[82:83], v[88:89] op_sel_hi:[1,0,1]
	s_nop 0
	v_mov_b32_e32 v82, v85
	v_pk_mul_f32 v[88:89], v[62:63], v[82:83] op_sel:[1,0] op_sel_hi:[0,0]
	v_pk_fma_f32 v[92:93], v[62:63], v[84:85], v[88:89] neg_lo:[0,0,1] neg_hi:[0,0,1]
	v_pk_fma_f32 v[84:85], v[62:63], v[84:85], v[88:89] op_sel_hi:[1,0,1]
	v_pk_mul_f32 v[88:89], v[56:57], v[78:79] op_sel:[1,1] op_sel_hi:[0,1]
	v_pk_fma_f32 v[94:95], v[56:57], v[78:79], v[88:89] neg_lo:[0,0,1] neg_hi:[0,0,1]
	v_pk_fma_f32 v[88:89], v[56:57], v[78:79], v[88:89] op_sel_hi:[1,0,1]
	v_mov_b32_e32 v78, v81
	v_pk_mul_f32 v[78:79], v[58:59], v[78:79] op_sel:[1,0] op_sel_hi:[0,0]
	v_pk_fma_f32 v[96:97], v[58:59], v[80:81], v[78:79] neg_lo:[0,0,1] neg_hi:[0,0,1]
	v_pk_fma_f32 v[80:81], v[58:59], v[80:81], v[78:79] op_sel_hi:[1,0,1]
	v_cvt_pk_bf16_f32 v78, v90, v83
	v_cvt_pk_bf16_f32 v79, v92, v85
	v_cvt_pk_bf16_f32 v80, v94, v89
	v_cvt_pk_bf16_f32 v81, v96, v81
	v_lshl_add_u64 v[82:83], v[146:147], 0, v[86:87]
	global_store_dwordx4 v[82:83], v[78:81], off

; DI void ss_add(ssacc_t* p, float v) { atomicAdd(p, (ssacc_t)__float2ull_rn(v * 4294967296.f)); }
; DI float quad_sum(float s) { s += __shfl_xor(s, 16); s += __shfl_xor(s, 32); return s; }
;     DI void operator()(const Acc& acc, const Unit& u, int wr, int wc, int fr, int fq) const {
;     ...
;                 if (pn <= 2) { sq = quad_sum(sq); if (fq == 0) ss_add((pn <= 1 ? ssq : sskv) + row, sq); }
.LBB0_454:
	v_mbcnt_hi_u32_b32 v49, -1, v189
	v_and_b32_e32 v50, 64, v49
	v_xor_b32_e32 v48, 16, v49
	v_add_u32_e32 v50, 64, v50
	v_cmp_lt_i32_e32 vcc, v48, v50
	v_xor_b32_e32 v51, 32, v49
	s_nop 0
	v_cndmask_b32_e32 v48, v49, v48, vcc
	v_lshlrev_b32_e32 v48, 2, v48
	ds_bpermute_b32 v48, v48, v56
	v_cmp_lt_i32_e32 vcc, v51, v50
	s_waitcnt lgkmcnt(0)
	v_add_f32_e32 v48, v56, v48
	v_cndmask_b32_e32 v49, v49, v51, vcc
	v_lshlrev_b32_e32 v49, 2, v49
	ds_bpermute_b32 v49, v49, v48
	s_and_saveexec_b64 s[6:7], s[46:47]
	s_cbranch_execz .LBB0_456
	s_waitcnt lgkmcnt(0)
	v_add_f32_e32 v48, v48, v49
	v_mul_f32_e32 v48, 0x4f800000, v48
	v_rndne_f32_e32 v48, v48
	v_mul_f32_e32 v49, 0x2f800000, v48
	v_floor_f32_e32 v49, v49
	v_fmac_f32_e32 v48, 0xcf800000, v49
	v_cvt_u32_f32_e32 v48, v48
	v_cvt_u32_f32_e32 v49, v49
	v_mov_b32_e32 v236, v48
	v_mov_b32_e32 v237, v49

; DI float ss_get(const ssacc_t* p) { const ssacc_t v = *p; return (float)(unsigned)(v >> 32) + (float)(unsigned)(v & 0xffffffffull) * 2.3283064365386963e-10f; }
; DI float sq8(const f32x4& a, const f32x4& b) { return (a[0] * a[0] + a[1] * a[1]) + (a[2] * a[2] + a[3] * a[3]) + (b[0] * b[0] + b[1] * b[1]) + (b[2] * b[2] + b[3] * b[3]); }
; DI u32x4 pack8(const f32x4& a, const f32x4& b) { u32x4 w; w.x = cvtpk(a[0], a[1]); w.y = cvtpk(a[2], a[3]); w.z = cvtpk(b[0], b[1]); w.w = cvtpk(b[2], b[3]); return w; }
;     DI const bf16_t* KPE() const { return (const bf16_t*)(ws + WS_KPE); }
;     DI const bf16_t* QD() const { return (const bf16_t*)(ws + WS_QD); }
;     DI const bf16_t* KD() const { return (const bf16_t*)(ws + WS_KD); }
;     DI const bf16_t* VD() const { return (const bf16_t*)(ws + WS_VD); }
; #define U WSF(WS_U)
; #define U WSF(WS_U)
;     DI void operator()(const Acc& acc, const Unit& u, int wr, int wc, int fr, int fq) const {
;     ...
;             for (int m = 0; m < 4; ++m) {
;                 asm volatile("" ::: "memory");
;                 const int row = u.pm * 256 + ai * 128 + wr * 64 + m * 16 + fr;
;                 const float rs = rsqrtf(ss_get(ssx + row) * (1.f / 2048.f) + EPS_);
;                 float sq = 0.f;
; #pragma unroll
;                 for (int bj = 0; bj < 2; ++bj) {
;                     f32x4 v0 = acc[ai][bj][m][0] * rs, v1 = acc[ai][bj][m][1] * rs;
;                     const int ct = bj * 128 + wc * 32 + 8 * fq;
;                     if (pn <= 1) { *(u32x4*)(CQ + (size_t)row * 512 + pn * 256 + ct) = pack8(v0, v1); sq += sq8(v0, v1); }
;                     else if (pn == 2) { *(u32x4*)(CKV + (size_t)row * 256 + ct) = pack8(v0, v1); sq += sq8(v0, v1); }
;                     else if (pn <= 4) { float* p = U + (size_t)row * 512 + (pn - 3) * 256 + ct; *(f32x4*)p = v0; *(f32x4*)(p + 4) = v1; }
;                     else if (pn <= 6) { v0 = v0 * QSCALE_DIL; v1 = v1 * QSCALE_DIL; *(u32x4*)(QD + (size_t)row * 512 + (pn - 5) * 256 + ct) = pack8(v0, v1); }
;                     else if (pn <= 8) { *(u32x4*)(KD + (size_t)row * 512 + (pn - 7) * 256 + ct) = pack8(v0, v1); }
;                     else if (pn <= 10) { *(u32x4*)(VD + (size_t)row * 512 + (pn - 9) * 256 + ct) = pack8(v0, v1); }
;                     else { if (ct < 64) { rope8(v0, v1, rope, row & 2047, ct >> 1); *(u32x4*)(KPE + (size_t)row * 64 + ct) = pack8(v0, v1); } }
.LBB0_457:
	s_waitcnt lgkmcnt(0)
	v_add_u32_e32 v62, 0x90, v152
	v_ashrrev_i32_e32 v63, 31, v62
	v_lshlrev_b64 v[52:53], 9, v[62:63]
	v_lshlrev_b64 v[60:61], 10, v[62:63]
	v_lshl_add_u64 v[58:59], s[84:85], 0, v[60:61]
	s_mov_b64 s[6:7], 0x1fafee00
	v_lshl_add_u64 v[56:57], v[58:59], 0, s[6:7]
	s_mov_b64 s[14:15], 0x1f2ff200
	v_lshlrev_b64 v[50:51], 11, v[62:63]
	v_lshl_add_u64 v[50:51], s[86:87], 0, v[50:51]
	s_and_b64 vcc, exec, s[52:53]
	s_waitcnt vmcnt(2)
	v_mov_b32_e32 v48, v222
	v_mov_b32_e32 v49, v223
	v_mov_b32_e32 v128, v49
	v_lshlrev_b64 v[54:55], s40, v[128:129]
	v_min_u32_e32 v49, 1, v54
	v_or_b32_e32 v49, v55, v49
	v_cvt_f32_u32_e32 v54, v49
	v_cvt_f32_u32_e32 v55, v48
	v_lshl_add_u64 v[48:49], s[66:67], 0, v[52:53]
	v_ldexp_f32 v52, v54, s38
	v_fmac_f32_e32 v52, 0x2f800000, v55
	v_fmamk_f32 v52, v52, 0x3a000000, v195
	v_mul_f32_e32 v53, 0x4b800000, v52
	v_cmp_gt_f32_e64 s[6:7], s27, v52
	v_lshl_add_u64 v[54:55], v[58:59], 0, s[14:15]
	s_mov_b64 s[14:15], 0x1eaff600
	v_cndmask_b32_e64 v52, v52, v53, s[6:7]
	v_rsq_f32_e32 v64, v52
	v_lshl_add_u64 v[52:53], v[58:59], 0, s[14:15]
	s_mov_b64 s[14:15], 0x1daff400
	v_lshl_add_u64 v[50:51], v[50:51], 0, s[14:15]
	v_mul_f32_e32 v58, 0x45800000, v64
	v_cndmask_b32_e64 v58, v64, v58, s[6:7]
	v_pk_mul_f32 v[46:47], v[46:47], v[58:59] op_sel_hi:[1,0]
	v_pk_mul_f32 v[44:45], v[44:45], v[58:59] op_sel_hi:[1,0]
	v_pk_mul_f32 v[42:43], v[42:43], v[58:59] op_sel_hi:[1,0]
	v_pk_mul_f32 v[40:41], v[40:41], v[58:59] op_sel_hi:[1,0]
	s_mov_b64 s[6:7], -1
	s_cbranch_vccnz .LBB0_481
	s_and_b64 vcc, exec, s[50:51]
	s_cbranch_vccnz .LBB0_478
	s_andn2_b64 vcc, exec, s[78:79]
	s_cbranch_vccnz .LBB0_475
	s_andn2_b64 vcc, exec, s[76:77]
	s_cbranch_vccnz .LBB0_472
	s_andn2_b64 vcc, exec, s[74:75]
	s_cbranch_vccnz .LBB0_469
	s_andn2_b64 vcc, exec, s[82:83]
	s_cbranch_vccnz .LBB0_466
	v_readlane_b32 s6, v255, 1
	v_readlane_b32 s7, v255, 2
	s_andn2_b64 vcc, exec, s[6:7]
	s_cbranch_vccnz .LBB0_465
	v_lshlrev_b32_e32 v59, 8, v62
	s_mov_b32 s4, 0x7df00
	v_readlane_b32 s6, v255, 3
	v_and_or_b32 v59, v59, s4, v170
	v_readlane_b32 s7, v255, 4
	v_lshlrev_b64 v[70:71], 7, v[62:63]
	s_nop 3
	global_load_dwordx4 v[62:65], v59, s[6:7] offset:16
	global_load_dwordx4 v[66:69], v59, s[6:7]
	s_waitcnt vmcnt(0)
	v_pk_mul_f32 v[72:73], v[44:45], v[66:67] op_sel:[1,1] op_sel_hi:[0,1]
	v_pk_fma_f32 v[74:75], v[44:45], v[66:67], v[72:73] neg_lo:[0,0,1] neg_hi:[0,0,1]
	v_pk_fma_f32 v[66:67], v[44:45], v[66:67], v[72:73] op_sel_hi:[1,0,1]
	s_nop 0
	v_mov_b32_e32 v66, v69
	v_pk_mul_f32 v[72:73], v[46:47], v[66:67] op_sel:[1,0] op_sel_hi:[0,0]
	v_pk_fma_f32 v[76:77], v[46:47], v[68:69], v[72:73] neg_lo:[0,0,1] neg_hi:[0,0,1]
	v_pk_fma_f32 v[68:69], v[46:47], v[68:69], v[72:73] op_sel_hi:[1,0,1]
	v_pk_mul_f32 v[72:73], v[40:41], v[62:63] op_sel:[1,1] op_sel_hi:[0,1]
	v_pk_fma_f32 v[78:79], v[40:41], v[62:63], v[72:73] neg_lo:[0,0,1] neg_hi:[0,0,1]
	v_pk_fma_f32 v[72:73], v[40:41], v[62:63], v[72:73] op_sel_hi:[1,0,1]
	v_mov_b32_e32 v62, v65
	v_pk_mul_f32 v[62:63], v[42:43], v[62:63] op_sel:[1,0] op_sel_hi:[0,0]
	v_pk_fma_f32 v[80:81], v[42:43], v[64:65], v[62:63] neg_lo:[0,0,1] neg_hi:[0,0,1]
	v_pk_fma_f32 v[64:65], v[42:43], v[64:65], v[62:63] op_sel_hi:[1,0,1]
	v_cvt_pk_bf16_f32 v62, v74, v67
	v_cvt_pk_bf16_f32 v63, v76, v69
	v_cvt_pk_bf16_f32 v64, v78, v73
	v_cvt_pk_bf16_f32 v65, v80, v65
	v_lshl_add_u64 v[66:67], v[146:147], 0, v[70:71]
	global_store_dwordx4 v[66:67], v[62:65], off

; DI void ss_add(ssacc_t* p, float v) { atomicAdd(p, (ssacc_t)__float2ull_rn(v * 4294967296.f)); }
; DI float quad_sum(float s) { s += __shfl_xor(s, 16); s += __shfl_xor(s, 32); return s; }
;     DI void operator()(const Acc& acc, const Unit& u, int wr, int wc, int fr, int fq) const {
;     ...
;                 if (pn <= 2) { sq = quad_sum(sq); if (fq == 0) ss_add((pn <= 1 ? ssq : sskv) + row, sq); }
.LBB0_506:
	v_mbcnt_hi_u32_b32 v33, -1, v189
	v_and_b32_e32 v34, 64, v33
	v_xor_b32_e32 v32, 16, v33
	v_add_u32_e32 v34, 64, v34
	v_cmp_lt_i32_e32 vcc, v32, v34
	v_xor_b32_e32 v35, 32, v33
	s_nop 0
	v_cndmask_b32_e32 v32, v33, v32, vcc
	v_lshlrev_b32_e32 v32, 2, v32
	ds_bpermute_b32 v32, v32, v40
	v_cmp_lt_i32_e32 vcc, v35, v34
	s_waitcnt lgkmcnt(0)
	v_add_f32_e32 v32, v40, v32
	v_cndmask_b32_e32 v33, v33, v35, vcc
	v_lshlrev_b32_e32 v33, 2, v33
	ds_bpermute_b32 v33, v33, v32
	s_and_saveexec_b64 s[6:7], s[46:47]
	s_cbranch_execz .LBB0_508
	s_waitcnt lgkmcnt(0)
	v_add_f32_e32 v32, v32, v33
	v_mul_f32_e32 v32, 0x4f800000, v32
	v_rndne_f32_e32 v32, v32
	v_mul_f32_e32 v33, 0x2f800000, v32
	v_floor_f32_e32 v33, v33
	v_fmac_f32_e32 v32, 0xcf800000, v33
	v_cvt_u32_f32_e32 v32, v32
	v_cvt_u32_f32_e32 v33, v33
	v_mov_b32_e32 v238, v32
	v_mov_b32_e32 v239, v33

; DI float ss_get(const ssacc_t* p) { const ssacc_t v = *p; return (float)(unsigned)(v >> 32) + (float)(unsigned)(v & 0xffffffffull) * 2.3283064365386963e-10f; }
; DI float sq8(const f32x4& a, const f32x4& b) { return (a[0] * a[0] + a[1] * a[1]) + (a[2] * a[2] + a[3] * a[3]) + (b[0] * b[0] + b[1] * b[1]) + (b[2] * b[2] + b[3] * b[3]); }
; DI u32x4 pack8(const f32x4& a, const f32x4& b) { u32x4 w; w.x = cvtpk(a[0], a[1]); w.y = cvtpk(a[2], a[3]); w.z = cvtpk(b[0], b[1]); w.w = cvtpk(b[2], b[3]); return w; }
;     DI const bf16_t* KPE() const { return (const bf16_t*)(ws + WS_KPE); }
;     DI const bf16_t* QD() const { return (const bf16_t*)(ws + WS_QD); }
;     DI const bf16_t* KD() const { return (const bf16_t*)(ws + WS_KD); }
;     DI const bf16_t* VD() const { return (const bf16_t*)(ws + WS_VD); }
; #define U WSF(WS_U)
; #define U WSF(WS_U)
;     DI void operator()(const Acc& acc, const Unit& u, int wr, int wc, int fr, int fq) const {
;     ...
;             for (int m = 0; m < 4; ++m) {
;                 asm volatile("" ::: "memory");
;                 const int row = u.pm * 256 + ai * 128 + wr * 64 + m * 16 + fr;
;                 const float rs = rsqrtf(ss_get(ssx + row) * (1.f / 2048.f) + EPS_);
;                 float sq = 0.f;
; #pragma unroll
;                 for (int bj = 0; bj < 2; ++bj) {
;                     f32x4 v0 = acc[ai][bj][m][0] * rs, v1 = acc[ai][bj][m][1] * rs;
;                     const int ct = bj * 128 + wc * 32 + 8 * fq;
;                     if (pn <= 1) { *(u32x4*)(CQ + (size_t)row * 512 + pn * 256 + ct) = pack8(v0, v1); sq += sq8(v0, v1); }
;                     else if (pn == 2) { *(u32x4*)(CKV + (size_t)row * 256 + ct) = pack8(v0, v1); sq += sq8(v0, v1); }
;                     else if (pn <= 4) { float* p = U + (size_t)row * 512 + (pn - 3) * 256 + ct; *(f32x4*)p = v0; *(f32x4*)(p + 4) = v1; }
;                     else if (pn <= 6) { v0 = v0 * QSCALE_DIL; v1 = v1 * QSCALE_DIL; *(u32x4*)(QD + (size_t)row * 512 + (pn - 5) * 256 + ct) = pack8(v0, v1); }
;                     else if (pn <= 8) { *(u32x4*)(KD + (size_t)row * 512 + (pn - 7) * 256 + ct) = pack8(v0, v1); }
;                     else if (pn <= 10) { *(u32x4*)(VD + (size_t)row * 512 + (pn - 9) * 256 + ct) = pack8(v0, v1); }
;                     else { if (ct < 64) { rope8(v0, v1, rope, row & 2047, ct >> 1); *(u32x4*)(KPE + (size_t)row * 64 + ct) = pack8(v0, v1); } }
.LBB0_509:
	s_waitcnt lgkmcnt(0)
	v_add_u32_e32 v46, 0xa0, v152
	v_ashrrev_i32_e32 v47, 31, v46
	v_lshlrev_b64 v[36:37], 9, v[46:47]
	v_lshlrev_b64 v[44:45], 10, v[46:47]
	v_lshl_add_u64 v[42:43], s[84:85], 0, v[44:45]
	s_mov_b64 s[6:7], 0x1fafee00
	v_lshl_add_u64 v[40:41], v[42:43], 0, s[6:7]
	s_mov_b64 s[14:15], 0x1f2ff200
	v_lshlrev_b64 v[34:35], 11, v[46:47]
	v_lshl_add_u64 v[34:35], s[86:87], 0, v[34:35]
	s_and_b64 vcc, exec, s[52:53]
	s_waitcnt vmcnt(1)
	v_mov_b32_e32 v32, v224
	v_mov_b32_e32 v33, v225
	v_mov_b32_e32 v128, v33
	v_lshlrev_b64 v[38:39], s40, v[128:129]
	v_min_u32_e32 v33, 1, v38
	v_or_b32_e32 v33, v39, v33
	v_cvt_f32_u32_e32 v38, v33
	v_cvt_f32_u32_e32 v39, v32
	v_lshl_add_u64 v[32:33], s[66:67], 0, v[36:37]
	v_ldexp_f32 v36, v38, s38
	v_fmac_f32_e32 v36, 0x2f800000, v39
	v_fmamk_f32 v36, v36, 0x3a000000, v195
	v_mul_f32_e32 v37, 0x4b800000, v36
	v_cmp_gt_f32_e64 s[6:7], s27, v36
	v_lshl_add_u64 v[38:39], v[42:43], 0, s[14:15]
	s_mov_b64 s[14:15], 0x1eaff600
	v_cndmask_b32_e64 v36, v36, v37, s[6:7]
	v_rsq_f32_e32 v48, v36
	v_lshl_add_u64 v[36:37], v[42:43], 0, s[14:15]
	s_mov_b64 s[14:15], 0x1daff400
	v_lshl_add_u64 v[34:35], v[34:35], 0, s[14:15]
	v_mul_f32_e32 v42, 0x45800000, v48
	v_cndmask_b32_e64 v42, v48, v42, s[6:7]
	v_pk_mul_f32 v[30:31], v[30:31], v[42:43] op_sel_hi:[1,0]
	v_pk_mul_f32 v[28:29], v[28:29], v[42:43] op_sel_hi:[1,0]
	v_pk_mul_f32 v[26:27], v[26:27], v[42:43] op_sel_hi:[1,0]
	v_pk_mul_f32 v[24:25], v[24:25], v[42:43] op_sel_hi:[1,0]
	s_mov_b64 s[6:7], -1
	s_cbranch_vccnz .LBB0_533
	s_and_b64 vcc, exec, s[50:51]
	s_cbranch_vccnz .LBB0_530
	s_andn2_b64 vcc, exec, s[78:79]
	s_cbranch_vccnz .LBB0_527
	s_andn2_b64 vcc, exec, s[76:77]
	s_cbranch_vccnz .LBB0_524
	s_andn2_b64 vcc, exec, s[74:75]
	s_cbranch_vccnz .LBB0_521
	s_andn2_b64 vcc, exec, s[82:83]
	s_cbranch_vccnz .LBB0_518
	v_readlane_b32 s6, v255, 1
	v_readlane_b32 s7, v255, 2
	s_andn2_b64 vcc, exec, s[6:7]
	s_cbranch_vccnz .LBB0_517
	v_lshlrev_b32_e32 v43, 8, v46
	s_mov_b32 s4, 0x7ef00
	v_readlane_b32 s6, v255, 3
	v_and_or_b32 v43, v43, s4, v170
	v_readlane_b32 s7, v255, 4
	v_lshlrev_b64 v[54:55], 7, v[46:47]
	s_nop 3
	global_load_dwordx4 v[46:49], v43, s[6:7] offset:16
	global_load_dwordx4 v[50:53], v43, s[6:7]
	s_waitcnt vmcnt(0)
	v_pk_mul_f32 v[56:57], v[28:29], v[50:51] op_sel:[1,1] op_sel_hi:[0,1]
	v_pk_fma_f32 v[58:59], v[28:29], v[50:51], v[56:57] neg_lo:[0,0,1] neg_hi:[0,0,1]
	v_pk_fma_f32 v[50:51], v[28:29], v[50:51], v[56:57] op_sel_hi:[1,0,1]
	s_nop 0
	v_mov_b32_e32 v50, v53
	v_pk_mul_f32 v[56:57], v[30:31], v[50:51] op_sel:[1,0] op_sel_hi:[0,0]
	v_pk_fma_f32 v[60:61], v[30:31], v[52:53], v[56:57] neg_lo:[0,0,1] neg_hi:[0,0,1]
	v_pk_fma_f32 v[52:53], v[30:31], v[52:53], v[56:57] op_sel_hi:[1,0,1]
	v_pk_mul_f32 v[56:57], v[24:25], v[46:47] op_sel:[1,1] op_sel_hi:[0,1]
	v_pk_fma_f32 v[62:63], v[24:25], v[46:47], v[56:57] neg_lo:[0,0,1] neg_hi:[0,0,1]
	v_pk_fma_f32 v[56:57], v[24:25], v[46:47], v[56:57] op_sel_hi:[1,0,1]
	v_mov_b32_e32 v46, v49
	v_pk_mul_f32 v[46:47], v[26:27], v[46:47] op_sel:[1,0] op_sel_hi:[0,0]
	v_pk_fma_f32 v[64:65], v[26:27], v[48:49], v[46:47] neg_lo:[0,0,1] neg_hi:[0,0,1]
	v_pk_fma_f32 v[48:49], v[26:27], v[48:49], v[46:47] op_sel_hi:[1,0,1]
	v_cvt_pk_bf16_f32 v46, v58, v51
	v_cvt_pk_bf16_f32 v47, v60, v53
	v_cvt_pk_bf16_f32 v48, v62, v57
	v_cvt_pk_bf16_f32 v49, v64, v49
	v_lshl_add_u64 v[50:51], v[146:147], 0, v[54:55]
	global_store_dwordx4 v[50:51], v[46:49], off

; DI void ss_add(ssacc_t* p, float v) { atomicAdd(p, (ssacc_t)__float2ull_rn(v * 4294967296.f)); }
; DI float quad_sum(float s) { s += __shfl_xor(s, 16); s += __shfl_xor(s, 32); return s; }
;     DI void operator()(const Acc& acc, const Unit& u, int wr, int wc, int fr, int fq) const {
;     ...
;                 if (pn <= 2) { sq = quad_sum(sq); if (fq == 0) ss_add((pn <= 1 ? ssq : sskv) + row, sq); }
.LBB0_558:
	v_mbcnt_hi_u32_b32 v17, -1, v189
	v_and_b32_e32 v18, 64, v17
	v_xor_b32_e32 v16, 16, v17
	v_add_u32_e32 v18, 64, v18
	v_cmp_lt_i32_e32 vcc, v16, v18
	v_xor_b32_e32 v19, 32, v17
	s_nop 0
	v_cndmask_b32_e32 v16, v17, v16, vcc
	v_lshlrev_b32_e32 v16, 2, v16
	ds_bpermute_b32 v16, v16, v24
	v_cmp_lt_i32_e32 vcc, v19, v18
	s_waitcnt lgkmcnt(0)
	v_add_f32_e32 v16, v24, v16
	v_cndmask_b32_e32 v17, v17, v19, vcc
	v_lshlrev_b32_e32 v17, 2, v17
	ds_bpermute_b32 v17, v17, v16
	s_and_saveexec_b64 s[6:7], s[46:47]
	s_cbranch_execz .LBB0_560
	s_waitcnt lgkmcnt(0)
	v_add_f32_e32 v16, v16, v17
	v_mul_f32_e32 v16, 0x4f800000, v16
	v_rndne_f32_e32 v16, v16
	v_mul_f32_e32 v17, 0x2f800000, v16
	v_floor_f32_e32 v17, v17
	v_fmac_f32_e32 v16, 0xcf800000, v17
	v_cvt_u32_f32_e32 v16, v16
	v_cvt_u32_f32_e32 v17, v17
	v_mov_b32_e32 v240, v16
	v_mov_b32_e32 v241, v17

; DI float ss_get(const ssacc_t* p) { const ssacc_t v = *p; return (float)(unsigned)(v >> 32) + (float)(unsigned)(v & 0xffffffffull) * 2.3283064365386963e-10f; }
; DI float sq8(const f32x4& a, const f32x4& b) { return (a[0] * a[0] + a[1] * a[1]) + (a[2] * a[2] + a[3] * a[3]) + (b[0] * b[0] + b[1] * b[1]) + (b[2] * b[2] + b[3] * b[3]); }
; DI u32x4 pack8(const f32x4& a, const f32x4& b) { u32x4 w; w.x = cvtpk(a[0], a[1]); w.y = cvtpk(a[2], a[3]); w.z = cvtpk(b[0], b[1]); w.w = cvtpk(b[2], b[3]); return w; }
;     DI const bf16_t* KPE() const { return (const bf16_t*)(ws + WS_KPE); }
;     DI const bf16_t* QD() const { return (const bf16_t*)(ws + WS_QD); }
;     DI const bf16_t* KD() const { return (const bf16_t*)(ws + WS_KD); }
;     DI const bf16_t* VD() const { return (const bf16_t*)(ws + WS_VD); }
; #define U WSF(WS_U)
; #define U WSF(WS_U)
;     DI void operator()(const Acc& acc, const Unit& u, int wr, int wc, int fr, int fq) const {
;     ...
;             for (int m = 0; m < 4; ++m) {
;                 asm volatile("" ::: "memory");
;                 const int row = u.pm * 256 + ai * 128 + wr * 64 + m * 16 + fr;
;                 const float rs = rsqrtf(ss_get(ssx + row) * (1.f / 2048.f) + EPS_);
;                 float sq = 0.f;
; #pragma unroll
;                 for (int bj = 0; bj < 2; ++bj) {
;                     f32x4 v0 = acc[ai][bj][m][0] * rs, v1 = acc[ai][bj][m][1] * rs;
;                     const int ct = bj * 128 + wc * 32 + 8 * fq;
;                     if (pn <= 1) { *(u32x4*)(CQ + (size_t)row * 512 + pn * 256 + ct) = pack8(v0, v1); sq += sq8(v0, v1); }
;                     else if (pn == 2) { *(u32x4*)(CKV + (size_t)row * 256 + ct) = pack8(v0, v1); sq += sq8(v0, v1); }
;                     else if (pn <= 4) { float* p = U + (size_t)row * 512 + (pn - 3) * 256 + ct; *(f32x4*)p = v0; *(f32x4*)(p + 4) = v1; }
;                     else if (pn <= 6) { v0 = v0 * QSCALE_DIL; v1 = v1 * QSCALE_DIL; *(u32x4*)(QD + (size_t)row * 512 + (pn - 5) * 256 + ct) = pack8(v0, v1); }
;                     else if (pn <= 8) { *(u32x4*)(KD + (size_t)row * 512 + (pn - 7) * 256 + ct) = pack8(v0, v1); }
;                     else if (pn <= 10) { *(u32x4*)(VD + (size_t)row * 512 + (pn - 9) * 256 + ct) = pack8(v0, v1); }
;                     else { if (ct < 64) { rope8(v0, v1, rope, row & 2047, ct >> 1); *(u32x4*)(KPE + (size_t)row * 64 + ct) = pack8(v0, v1); } }
.LBB0_561:
	s_waitcnt lgkmcnt(0)
	v_add_u32_e32 v30, 0xb0, v152
	v_ashrrev_i32_e32 v31, 31, v30
	v_lshlrev_b64 v[20:21], 9, v[30:31]
	v_lshlrev_b64 v[28:29], 10, v[30:31]
	v_lshl_add_u64 v[26:27], s[84:85], 0, v[28:29]
	s_mov_b64 s[6:7], 0x1fafee00
	v_lshl_add_u64 v[24:25], v[26:27], 0, s[6:7]
	s_mov_b64 s[14:15], 0x1f2ff200
	v_lshlrev_b64 v[18:19], 11, v[30:31]
	v_lshl_add_u64 v[18:19], s[86:87], 0, v[18:19]
	s_and_b64 vcc, exec, s[52:53]
	s_waitcnt vmcnt(0)
	v_mov_b32_e32 v16, v226
	v_mov_b32_e32 v17, v227
	v_mov_b32_e32 v128, v17
	v_lshlrev_b64 v[22:23], s40, v[128:129]
	v_min_u32_e32 v17, 1, v22
	v_or_b32_e32 v17, v23, v17
	v_cvt_f32_u32_e32 v22, v17
	v_cvt_f32_u32_e32 v23, v16
	v_lshl_add_u64 v[16:17], s[66:67], 0, v[20:21]
	v_ldexp_f32 v20, v22, s38
	v_fmac_f32_e32 v20, 0x2f800000, v23
	v_fmamk_f32 v20, v20, 0x3a000000, v195
	v_mul_f32_e32 v21, 0x4b800000, v20
	v_cmp_gt_f32_e64 s[6:7], s27, v20
	v_lshl_add_u64 v[22:23], v[26:27], 0, s[14:15]
	s_mov_b64 s[14:15], 0x1eaff600
	v_cndmask_b32_e64 v20, v20, v21, s[6:7]
	v_rsq_f32_e32 v32, v20
	v_lshl_add_u64 v[20:21], v[26:27], 0, s[14:15]
	s_mov_b64 s[14:15], 0x1daff400
	v_lshl_add_u64 v[18:19], v[18:19], 0, s[14:15]
	v_mul_f32_e32 v26, 0x45800000, v32
	v_cndmask_b32_e64 v26, v32, v26, s[6:7]
	v_pk_mul_f32 v[14:15], v[14:15], v[26:27] op_sel_hi:[1,0]
	v_pk_mul_f32 v[12:13], v[12:13], v[26:27] op_sel_hi:[1,0]
	v_pk_mul_f32 v[10:11], v[10:11], v[26:27] op_sel_hi:[1,0]
	v_pk_mul_f32 v[8:9], v[8:9], v[26:27] op_sel_hi:[1,0]
	s_mov_b64 s[6:7], -1
	s_cbranch_vccnz .LBB0_585
	s_and_b64 vcc, exec, s[50:51]
	s_cbranch_vccnz .LBB0_582
	s_andn2_b64 vcc, exec, s[78:79]
	s_cbranch_vccnz .LBB0_579
	s_andn2_b64 vcc, exec, s[76:77]
	s_cbranch_vccnz .LBB0_576
	s_andn2_b64 vcc, exec, s[74:75]
	s_cbranch_vccnz .LBB0_573
	s_andn2_b64 vcc, exec, s[82:83]
	s_cbranch_vccnz .LBB0_570
	v_readlane_b32 s6, v255, 1
	v_readlane_b32 s7, v255, 2
	s_andn2_b64 vcc, exec, s[6:7]
	s_cbranch_vccnz .LBB0_569
	v_lshlrev_b32_e32 v27, 8, v30
	s_mov_b32 s4, 0x7ff00
	v_readlane_b32 s6, v255, 3
	v_and_or_b32 v27, v27, s4, v170
	v_readlane_b32 s7, v255, 4
	v_lshlrev_b64 v[38:39], 7, v[30:31]
	s_nop 3
	global_load_dwordx4 v[30:33], v27, s[6:7] offset:16
	global_load_dwordx4 v[34:37], v27, s[6:7]
	s_waitcnt vmcnt(0)
	v_pk_mul_f32 v[40:41], v[12:13], v[34:35] op_sel:[1,1] op_sel_hi:[0,1]
	v_pk_fma_f32 v[42:43], v[12:13], v[34:35], v[40:41] neg_lo:[0,0,1] neg_hi:[0,0,1]
	v_pk_fma_f32 v[34:35], v[12:13], v[34:35], v[40:41] op_sel_hi:[1,0,1]
	s_nop 0
	v_mov_b32_e32 v34, v37
	v_pk_mul_f32 v[40:41], v[14:15], v[34:35] op_sel:[1,0] op_sel_hi:[0,0]
	v_pk_fma_f32 v[44:45], v[14:15], v[36:37], v[40:41] neg_lo:[0,0,1] neg_hi:[0,0,1]
	v_pk_fma_f32 v[36:37], v[14:15], v[36:37], v[40:41] op_sel_hi:[1,0,1]
	v_pk_mul_f32 v[40:41], v[8:9], v[30:31] op_sel:[1,1] op_sel_hi:[0,1]
	v_pk_fma_f32 v[46:47], v[8:9], v[30:31], v[40:41] neg_lo:[0,0,1] neg_hi:[0,0,1]
	v_pk_fma_f32 v[40:41], v[8:9], v[30:31], v[40:41] op_sel_hi:[1,0,1]
	v_mov_b32_e32 v30, v33
	v_pk_mul_f32 v[30:31], v[10:11], v[30:31] op_sel:[1,0] op_sel_hi:[0,0]
	v_pk_fma_f32 v[48:49], v[10:11], v[32:33], v[30:31] neg_lo:[0,0,1] neg_hi:[0,0,1]
	v_pk_fma_f32 v[32:33], v[10:11], v[32:33], v[30:31] op_sel_hi:[1,0,1]
	v_cvt_pk_bf16_f32 v30, v42, v35
	v_cvt_pk_bf16_f32 v31, v44, v37
	v_cvt_pk_bf16_f32 v32, v46, v41
	v_cvt_pk_bf16_f32 v33, v48, v33
	v_lshl_add_u64 v[34:35], v[146:147], 0, v[38:39]
	global_store_dwordx4 v[34:35], v[30:33], off

; DI void ss_add(ssacc_t* p, float v) { atomicAdd(p, (ssacc_t)__float2ull_rn(v * 4294967296.f)); }
; DI float quad_sum(float s) { s += __shfl_xor(s, 16); s += __shfl_xor(s, 32); return s; }
;     DI void operator()(const Acc& acc, const Unit& u, int wr, int wc, int fr, int fq) const {
;     ...
;                 if (pn <= 2) { sq = quad_sum(sq); if (fq == 0) ss_add((pn <= 1 ? ssq : sskv) + row, sq); }
.LBB0_610:
	v_mbcnt_hi_u32_b32 v1, -1, v189
	v_and_b32_e32 v2, 64, v1
	v_xor_b32_e32 v0, 16, v1
	v_add_u32_e32 v2, 64, v2
	v_cmp_lt_i32_e32 vcc, v0, v2
	v_xor_b32_e32 v3, 32, v1
	s_nop 0
	v_cndmask_b32_e32 v0, v1, v0, vcc
	v_lshlrev_b32_e32 v0, 2, v0
	ds_bpermute_b32 v0, v0, v8
	v_cmp_lt_i32_e32 vcc, v3, v2
	s_waitcnt lgkmcnt(0)
	v_add_f32_e32 v0, v8, v0
	v_cndmask_b32_e32 v1, v1, v3, vcc
	v_lshlrev_b32_e32 v1, 2, v1
	ds_bpermute_b32 v1, v1, v0
	s_and_saveexec_b64 s[6:7], s[46:47]
	s_cbranch_execz .LBB0_612
	s_waitcnt lgkmcnt(0)
	v_add_f32_e32 v0, v0, v1
	v_mul_f32_e32 v0, 0x4f800000, v0
	v_rndne_f32_e32 v0, v0
	v_mul_f32_e32 v1, 0x2f800000, v0
	v_floor_f32_e32 v1, v1
	v_fmac_f32_e32 v0, 0xcf800000, v1
	v_cvt_u32_f32_e32 v0, v0
	v_cvt_u32_f32_e32 v1, v1
	v_lshl_add_u64 v[2:3], v[152:153], 3, s[88:89]
	global_atomic_add_x2 v[2:3], v[228:229], off
	global_atomic_add_x2 v[2:3], v[230:231], off offset:128
	global_atomic_add_x2 v[2:3], v[232:233], off offset:256
	global_atomic_add_x2 v[2:3], v[234:235], off offset:384
	global_atomic_add_x2 v[2:3], v[236:237], off offset:1024
	global_atomic_add_x2 v[2:3], v[238:239], off offset:1152
	global_atomic_add_x2 v[2:3], v[240:241], off offset:1280
	global_atomic_add_x2 v[2:3], v[0:1], off offset:1408

; DI void ss_add(ssacc_t* p, float v) { atomicAdd(p, (ssacc_t)__float2ull_rn(v * 4294967296.f)); }
; DI unsigned cvtpk(float lo, float hi) { f32x2 v = {lo, hi}; bf16x2_t b = __builtin_convertvector(v, bf16x2_t); return __builtin_bit_cast(unsigned, b); }
; DI float sigmoidf_(float x) { return __builtin_amdgcn_rcpf(1.f + fexp2(-LOG2E * x)); }
; DI float quad_sum(float s) { s += __shfl_xor(s, 16); s += __shfl_xor(s, 32); return s; }
;     DI bf16_t* YCAT() const { return (bf16_t*)(ws + WS_YCAT); }
;     DI void operator()(const Acc& acc, const Unit& u, int wr, int wc, int fr, int fq) const {
; #pragma unroll
;         for (int ai = 0; ai < 2; ++ai)
; #pragma unroll
;             for (int m = 0; m < 4; ++m) {
;                 asm volatile("" ::: "memory");
;                 const int row = u.pm * 256 + ai * 128 + wr * 64 + m * 16 + fr;
;                 float sq = 0.f;
; #pragma unroll
;                 for (int bj = 0; bj < 2; ++bj) {
;                     const f32x4 v0 = acc[ai][bj][m][0], v1 = acc[ai][bj][m][1];
;                     const int i0 = (u.pn * 256 + bj * 128 + wc * 32 + 8 * fq) >> 1;
;                     const f32x4 b1 = *(const f32x4*)(bglu + i0), b2 = *(const f32x4*)(bglu + 512 + i0);
;                     const float o0 = (v0[0] + b1[0]) * sigmoidf_(v0[1] + b2[0]), o1 = (v0[2] + b1[1]) * sigmoidf_(v0[3] + b2[1]);
;                     const float o2 = (v1[0] + b1[2]) * sigmoidf_(v1[1] + b2[2]), o3 = (v1[2] + b1[3]) * sigmoidf_(v1[3] + b2[3]);
;                     sq += (o0 * o0 + o1 * o1) + (o2 * o2 + o3 * o3);
;                     u32x2 w; w.x = cvtpk(o0, o1); w.y = cvtpk(o2, o3);
;                     *(u32x2*)(YCAT + (size_t)row * 2048 + i0) = w;
;                 }
;                 sq = quad_sum(sq); if (fq == 0) ss_add(ss + row, sq);
;             }
;     }
.LBB0_1172:
	v_lshl_or_b32 v140, s68, 8, v148
	v_ashrrev_i32_e32 v142, 1, v140
	v_ashrrev_i32_e32 v143, 31, v142
	v_lshl_add_u64 v[140:141], v[142:143], 2, s[44:45]
	global_load_dwordx4 v[208:211], v[140:141], off offset:2048
	global_load_dwordx4 v[212:215], v[140:141], off
	global_load_dwordx4 v[216:219], v[140:141], off offset:2304
	global_load_dwordx4 v[220:223], v[140:141], off offset:256
	v_lshl_add_u32 v144, s67, 8, v146
	v_ashrrev_i32_e32 v145, 31, v144
	v_lshlrev_b64 v[158:159], 12, v[144:145]
	v_lshl_add_u64 v[158:159], s[52:53], 0, v[158:159]
	v_lshl_add_u64 v[158:159], v[142:143], 1, v[158:159]
	s_waitcnt vmcnt(2)
	v_mov_b32_e32 v150, v208
	v_mov_b32_e32 v151, v209
	v_mov_b32_e32 v152, v210
	v_mov_b32_e32 v153, v211
	v_mov_b32_e32 v154, v212
	v_mov_b32_e32 v155, v213
	v_mov_b32_e32 v156, v214
	v_mov_b32_e32 v157, v215
	v_add_f32_e32 v150, v121, v150
	v_add_f32_e32 v123, v123, v151
	v_mov_b32_e32 v121, v122
	v_add_f32_e32 v122, v125, v152
	v_add_f32_e32 v127, v127, v153
	v_mov_b32_e32 v125, v126
	v_mul_f32_e32 v126, 0xbfb8aa3b, v150
	v_mul_f32_e32 v123, 0xbfb8aa3b, v123
	v_mul_f32_e32 v122, 0xbfb8aa3b, v122
	v_mul_f32_e32 v127, 0xbfb8aa3b, v127
	v_exp_f32_e32 v126, v126
	v_exp_f32_e32 v123, v123
	v_exp_f32_e32 v122, v122
	v_exp_f32_e32 v127, v127
	v_add_f32_e32 v126, 1.0, v126
	v_add_f32_e32 v123, 1.0, v123
	v_add_f32_e32 v150, 1.0, v122
	v_add_f32_e32 v127, 1.0, v127
	v_rcp_f32_e32 v122, v126
	v_rcp_f32_e32 v123, v123
	v_rcp_f32_e32 v126, v150
	v_rcp_f32_e32 v127, v127
	v_pk_add_f32 v[120:121], v[120:121], v[154:155]
	v_pk_add_f32 v[124:125], v[124:125], v[156:157]
	v_pk_mul_f32 v[154:155], v[120:121], v[122:123]
	v_pk_mul_f32 v[126:127], v[124:125], v[126:127]
	v_cvt_pk_bf16_f32 v120, v154, v155
	v_cvt_pk_bf16_f32 v121, v126, v127
	global_store_dwordx2 v[158:159], v[120:121], off
	v_and_b32_e32 v121, 64, v199
	v_xor_b32_e32 v120, 16, v199
	v_add_u32_e32 v121, 64, v121
	v_pk_mul_f32 v[154:155], v[154:155], v[154:155]
	v_pk_mul_f32 v[126:127], v[126:127], v[126:127]
	v_cmp_lt_i32_e32 vcc, v120, v121
	v_add_f32_e32 v126, v126, v127
	v_add_f32_e32 v127, v154, v155
	v_cndmask_b32_e32 v120, v199, v120, vcc
	v_add_f32_e32 v126, v127, v126
	v_lshlrev_b32_e32 v120, 2, v120
	s_waitcnt vmcnt(1)
	v_mov_b32_e32 v122, v216
	v_mov_b32_e32 v123, v217
	v_mov_b32_e32 v124, v218
	v_mov_b32_e32 v125, v219
	v_mov_b32_e32 v150, v220
	v_mov_b32_e32 v151, v221
	v_mov_b32_e32 v152, v222
	v_mov_b32_e32 v153, v223
	v_add_f32_e32 v122, v117, v122
	v_add_f32_e32 v119, v119, v123
	v_mov_b32_e32 v117, v118
	v_add_f32_e32 v118, v113, v124
	v_add_f32_e32 v115, v115, v125
	v_mov_b32_e32 v113, v114
	v_mul_f32_e32 v114, 0xbfb8aa3b, v122
	v_mul_f32_e32 v119, 0xbfb8aa3b, v119
	v_mul_f32_e32 v118, 0xbfb8aa3b, v118
	v_mul_f32_e32 v115, 0xbfb8aa3b, v115
	v_exp_f32_e32 v114, v114
	v_exp_f32_e32 v119, v119
	v_exp_f32_e32 v118, v118
	v_exp_f32_e32 v115, v115
	v_add_f32_e32 v114, 1.0, v114
	v_add_f32_e32 v119, 1.0, v119
	v_add_f32_e32 v118, 1.0, v118
	v_add_f32_e32 v122, 1.0, v115
	v_rcp_f32_e32 v114, v114
	v_rcp_f32_e32 v115, v119
	v_rcp_f32_e32 v118, v118
	v_rcp_f32_e32 v119, v122
	v_pk_add_f32 v[116:117], v[116:117], v[150:151]
	v_pk_add_f32 v[112:113], v[112:113], v[152:153]
	v_pk_mul_f32 v[122:123], v[116:117], v[114:115]
	v_pk_mul_f32 v[112:113], v[112:113], v[118:119]
	v_pk_mul_f32 v[114:115], v[122:123], v[122:123]
	v_pk_mul_f32 v[116:117], v[112:113], v[112:113]
	v_add_f32_e32 v114, v114, v115
	v_add_f32_e32 v116, v116, v117
	v_add_f32_e32 v114, v114, v116
	v_add_f32_e32 v114, v126, v114
	ds_bpermute_b32 v115, v120, v114
	v_xor_b32_e32 v116, 32, v199
	v_cmp_lt_i32_e32 vcc, v116, v121
	v_cvt_pk_bf16_f32 v118, v122, v123
	v_cvt_pk_bf16_f32 v119, v112, v113
	v_cndmask_b32_e32 v116, v199, v116, vcc
	s_waitcnt lgkmcnt(0)
	v_add_f32_e32 v115, v114, v115
	v_lshlrev_b32_e32 v114, 2, v116
	ds_bpermute_b32 v116, v114, v115
	v_lshl_add_u64 v[112:113], v[144:145], 3, s[54:55]
	global_store_dwordx2 v[158:159], v[118:119], off offset:128
	s_and_saveexec_b64 s[14:15], s[48:49]
	s_cbranch_execz .LBB0_1174
	s_waitcnt lgkmcnt(0)
	v_add_f32_e32 v115, v115, v116
	v_mul_f32_e32 v115, 0x4f800000, v115
	v_rndne_f32_e32 v115, v115
	v_mul_f32_e32 v116, 0x2f800000, v115
	v_floor_f32_e32 v117, v116
	v_fmac_f32_e32 v115, 0xcf800000, v117
	v_cvt_u32_f32_e32 v116, v115
	v_cvt_u32_f32_e32 v117, v117
	v_mov_b32_e32 v160, v116
	v_mov_b32_e32 v161, v117
; DI void ss_add(ssacc_t* p, float v) { atomicAdd(p, (ssacc_t)__float2ull_rn(v * 4294967296.f)); }
; DI unsigned cvtpk(float lo, float hi) { f32x2 v = {lo, hi}; bf16x2_t b = __builtin_convertvector(v, bf16x2_t); return __builtin_bit_cast(unsigned, b); }
; DI float sigmoidf_(float x) { return __builtin_amdgcn_rcpf(1.f + fexp2(-LOG2E * x)); }
; DI float quad_sum(float s) { s += __shfl_xor(s, 16); s += __shfl_xor(s, 32); return s; }
;     DI bf16_t* YCAT() const { return (bf16_t*)(ws + WS_YCAT); }
;     DI void operator()(const Acc& acc, const Unit& u, int wr, int wc, int fr, int fq) const {
; #pragma unroll
;         for (int ai = 0; ai < 2; ++ai)
; #pragma unroll
;             for (int m = 0; m < 4; ++m) {
;                 asm volatile("" ::: "memory");
;                 const int row = u.pm * 256 + ai * 128 + wr * 64 + m * 16 + fr;
;                 float sq = 0.f;
; #pragma unroll
;                 for (int bj = 0; bj < 2; ++bj) {
;                     const f32x4 v0 = acc[ai][bj][m][0], v1 = acc[ai][bj][m][1];
;                     const int i0 = (u.pn * 256 + bj * 128 + wc * 32 + 8 * fq) >> 1;
;                     const f32x4 b1 = *(const f32x4*)(bglu + i0), b2 = *(const f32x4*)(bglu + 512 + i0);
;                     const float o0 = (v0[0] + b1[0]) * sigmoidf_(v0[1] + b2[0]), o1 = (v0[2] + b1[1]) * sigmoidf_(v0[3] + b2[1]);
;                     const float o2 = (v1[0] + b1[2]) * sigmoidf_(v1[1] + b2[2]), o3 = (v1[2] + b1[3]) * sigmoidf_(v1[3] + b2[3]);
;                     sq += (o0 * o0 + o1 * o1) + (o2 * o2 + o3 * o3);
;                     u32x2 w; w.x = cvtpk(o0, o1); w.y = cvtpk(o2, o3);
;                     *(u32x2*)(YCAT + (size_t)row * 2048 + i0) = w;
;                 }
;                 sq = quad_sum(sq); if (fq == 0) ss_add(ss + row, sq);
;             }
;     }
.LBB0_1174:
	s_or_b64 exec, exec, s[14:15]
	s_waitcnt lgkmcnt(0)
	v_or_b32_e32 v126, 16, v144
	v_ashrrev_i32_e32 v127, 31, v126
	v_lshlrev_b64 v[126:127], 12, v[126:127]
	v_lshl_add_u64 v[126:127], s[52:53], 0, v[126:127]
	v_lshl_add_u64 v[126:127], v[142:143], 1, v[126:127]
	v_mov_b32_e32 v116, v208
	v_mov_b32_e32 v117, v209
	v_mov_b32_e32 v118, v210
	v_mov_b32_e32 v119, v211
	v_mov_b32_e32 v122, v212
	v_mov_b32_e32 v123, v213
	v_mov_b32_e32 v124, v214
	v_mov_b32_e32 v125, v215
	v_add_f32_e32 v115, v109, v116
	v_add_f32_e32 v111, v111, v117
	v_mov_b32_e32 v109, v110
	v_add_f32_e32 v110, v105, v118
	v_add_f32_e32 v107, v107, v119
	v_mov_b32_e32 v105, v106
	v_mul_f32_e32 v106, 0xbfb8aa3b, v115
	v_mul_f32_e32 v111, 0xbfb8aa3b, v111
	v_mul_f32_e32 v110, 0xbfb8aa3b, v110
	v_mul_f32_e32 v107, 0xbfb8aa3b, v107
	v_exp_f32_e32 v106, v106
	v_exp_f32_e32 v111, v111
	v_exp_f32_e32 v110, v110
	v_exp_f32_e32 v107, v107
	v_add_f32_e32 v106, 1.0, v106
	v_add_f32_e32 v111, 1.0, v111
	v_add_f32_e32 v110, 1.0, v110
	v_add_f32_e32 v115, 1.0, v107
	v_rcp_f32_e32 v106, v106
	v_rcp_f32_e32 v107, v111
	v_rcp_f32_e32 v110, v110
	v_rcp_f32_e32 v111, v115
	v_pk_add_f32 v[108:109], v[108:109], v[122:123]
	v_pk_add_f32 v[104:105], v[104:105], v[124:125]
	v_pk_mul_f32 v[116:117], v[108:109], v[106:107]
	v_pk_mul_f32 v[118:119], v[104:105], v[110:111]
	v_cvt_pk_bf16_f32 v104, v116, v117
	v_cvt_pk_bf16_f32 v105, v118, v119
	global_store_dwordx2 v[126:127], v[104:105], off
	s_nop 0
	v_pk_mul_f32 v[116:117], v[116:117], v[116:117]
	v_pk_mul_f32 v[118:119], v[118:119], v[118:119]
	v_add_f32_e32 v116, v116, v117
	v_add_f32_e32 v115, v118, v119
	v_add_f32_e32 v115, v116, v115
	v_mov_b32_e32 v104, v216
	v_mov_b32_e32 v105, v217
	v_mov_b32_e32 v106, v218
	v_mov_b32_e32 v107, v219
	v_mov_b32_e32 v108, v220
	v_mov_b32_e32 v109, v221
	v_mov_b32_e32 v110, v222
	v_mov_b32_e32 v111, v223
	v_add_f32_e32 v104, v101, v104
	v_add_f32_e32 v103, v103, v105
	v_mov_b32_e32 v101, v102
	v_add_f32_e32 v102, v97, v106
	v_add_f32_e32 v99, v99, v107
	v_mov_b32_e32 v97, v98
	v_mul_f32_e32 v98, 0xbfb8aa3b, v104
	v_mul_f32_e32 v103, 0xbfb8aa3b, v103
	v_mul_f32_e32 v102, 0xbfb8aa3b, v102
	v_mul_f32_e32 v99, 0xbfb8aa3b, v99
	v_exp_f32_e32 v98, v98
	v_exp_f32_e32 v103, v103
	v_exp_f32_e32 v102, v102
	v_exp_f32_e32 v99, v99
	v_add_f32_e32 v98, 1.0, v98
	v_add_f32_e32 v103, 1.0, v103
	v_add_f32_e32 v102, 1.0, v102
	v_add_f32_e32 v104, 1.0, v99
	v_rcp_f32_e32 v98, v98
	v_rcp_f32_e32 v99, v103
	v_rcp_f32_e32 v102, v102
	v_rcp_f32_e32 v103, v104
	v_pk_add_f32 v[100:101], v[100:101], v[108:109]
	v_pk_add_f32 v[96:97], v[96:97], v[110:111]
	v_pk_mul_f32 v[98:99], v[100:101], v[98:99]
	v_pk_mul_f32 v[100:101], v[96:97], v[102:103]
	v_pk_mul_f32 v[96:97], v[98:99], v[98:99]
	v_pk_mul_f32 v[102:103], v[100:101], v[100:101]
	v_add_f32_e32 v96, v96, v97
	v_add_f32_e32 v102, v102, v103
	v_add_f32_e32 v96, v96, v102
	v_add_f32_e32 v96, v115, v96
	ds_bpermute_b32 v97, v120, v96
	v_cvt_pk_bf16_f32 v98, v98, v99
	v_cvt_pk_bf16_f32 v99, v100, v101
	global_store_dwordx2 v[126:127], v[98:99], off offset:128
	s_waitcnt lgkmcnt(0)
	v_add_f32_e32 v96, v96, v97
	ds_bpermute_b32 v97, v114, v96
	s_and_saveexec_b64 s[14:15], s[48:49]
	s_cbranch_execz .LBB0_1176
	s_waitcnt lgkmcnt(0)
	v_add_f32_e32 v96, v96, v97
	v_mul_f32_e32 v96, 0x4f800000, v96
	v_rndne_f32_e32 v96, v96
	v_mul_f32_e32 v97, 0x2f800000, v96
	v_floor_f32_e32 v97, v97
	v_fmac_f32_e32 v96, 0xcf800000, v97
	v_cvt_u32_f32_e32 v96, v96
	v_cvt_u32_f32_e32 v97, v97
	v_mov_b32_e32 v162, v96
	v_mov_b32_e32 v163, v97
.LBB0_1176:
	s_or_b64 exec, exec, s[14:15]
	s_waitcnt lgkmcnt(0)
	v_or_b32_e32 v104, 32, v144
	v_ashrrev_i32_e32 v105, 31, v104
	v_lshlrev_b64 v[104:105], 12, v[104:105]
	v_lshl_add_u64 v[104:105], s[52:53], 0, v[104:105]
	v_lshl_add_u64 v[104:105], v[142:143], 1, v[104:105]
	v_mov_b32_e32 v96, v208
	v_mov_b32_e32 v97, v209
	v_mov_b32_e32 v98, v210
	v_mov_b32_e32 v99, v211
	v_mov_b32_e32 v100, v212
	v_mov_b32_e32 v101, v213
	v_mov_b32_e32 v102, v214
	v_mov_b32_e32 v103, v215
	v_add_f32_e32 v96, v93, v96
	v_add_f32_e32 v95, v95, v97
	v_mov_b32_e32 v93, v94
	v_add_f32_e32 v94, v89, v98
	v_add_f32_e32 v91, v91, v99
	v_mov_b32_e32 v89, v90
	v_mul_f32_e32 v90, 0xbfb8aa3b, v96
	v_mul_f32_e32 v95, 0xbfb8aa3b, v95
	v_mul_f32_e32 v94, 0xbfb8aa3b, v94
	v_mul_f32_e32 v91, 0xbfb8aa3b, v91
	v_exp_f32_e32 v90, v90
	v_exp_f32_e32 v95, v95
	v_exp_f32_e32 v94, v94
	v_exp_f32_e32 v91, v91
	v_add_f32_e32 v90, 1.0, v90
	v_add_f32_e32 v95, 1.0, v95
	v_add_f32_e32 v94, 1.0, v94
	v_add_f32_e32 v96, 1.0, v91
	v_rcp_f32_e32 v90, v90
	v_rcp_f32_e32 v91, v95
	v_rcp_f32_e32 v94, v94
	v_rcp_f32_e32 v95, v96
	v_pk_add_f32 v[92:93], v[92:93], v[100:101]
	v_pk_add_f32 v[88:89], v[88:89], v[102:103]
	v_pk_mul_f32 v[96:97], v[92:93], v[90:91]
	v_pk_mul_f32 v[98:99], v[88:89], v[94:95]
	v_cvt_pk_bf16_f32 v88, v96, v97
	v_cvt_pk_bf16_f32 v89, v98, v99
	global_store_dwordx2 v[104:105], v[88:89], off
	s_nop 0
	v_pk_mul_f32 v[96:97], v[96:97], v[96:97]
	v_pk_mul_f32 v[98:99], v[98:99], v[98:99]
	v_add_f32_e32 v96, v96, v97
	v_add_f32_e32 v98, v98, v99
	v_add_f32_e32 v96, v96, v98
	v_mov_b32_e32 v88, v216
	v_mov_b32_e32 v89, v217
	v_mov_b32_e32 v90, v218
	v_mov_b32_e32 v91, v219
	v_mov_b32_e32 v92, v220
	v_mov_b32_e32 v93, v221
	v_mov_b32_e32 v94, v222
	v_mov_b32_e32 v95, v223
	v_add_f32_e32 v88, v85, v88
	v_add_f32_e32 v87, v87, v89
	v_mov_b32_e32 v85, v86
	v_add_f32_e32 v86, v81, v90
	v_add_f32_e32 v83, v83, v91
	v_mov_b32_e32 v81, v82
	v_mul_f32_e32 v82, 0xbfb8aa3b, v88
	v_mul_f32_e32 v87, 0xbfb8aa3b, v87
	v_mul_f32_e32 v86, 0xbfb8aa3b, v86
	v_mul_f32_e32 v83, 0xbfb8aa3b, v83
	v_exp_f32_e32 v82, v82
	v_exp_f32_e32 v87, v87
	v_exp_f32_e32 v86, v86
	v_exp_f32_e32 v83, v83
	v_add_f32_e32 v82, 1.0, v82
	v_add_f32_e32 v87, 1.0, v87
	v_add_f32_e32 v86, 1.0, v86
	v_add_f32_e32 v88, 1.0, v83
	v_rcp_f32_e32 v82, v82
	v_rcp_f32_e32 v83, v87
	v_rcp_f32_e32 v86, v86
	v_rcp_f32_e32 v87, v88
	v_pk_add_f32 v[84:85], v[84:85], v[92:93]
	v_pk_add_f32 v[80:81], v[80:81], v[94:95]
	v_pk_mul_f32 v[82:83], v[84:85], v[82:83]
	v_pk_mul_f32 v[84:85], v[80:81], v[86:87]
	v_pk_mul_f32 v[80:81], v[82:83], v[82:83]
	v_pk_mul_f32 v[86:87], v[84:85], v[84:85]
	v_add_f32_e32 v80, v80, v81
	v_add_f32_e32 v86, v86, v87
	v_add_f32_e32 v80, v80, v86
	v_add_f32_e32 v80, v96, v80
	ds_bpermute_b32 v81, v120, v80
	v_cvt_pk_bf16_f32 v82, v82, v83
	v_cvt_pk_bf16_f32 v83, v84, v85
	global_store_dwordx2 v[104:105], v[82:83], off offset:128
	s_waitcnt lgkmcnt(0)
	v_add_f32_e32 v80, v80, v81
	ds_bpermute_b32 v81, v114, v80
	s_and_saveexec_b64 s[14:15], s[48:49]
	s_cbranch_execz .LBB0_1178
	s_waitcnt lgkmcnt(0)
	v_add_f32_e32 v80, v80, v81
	v_mul_f32_e32 v80, 0x4f800000, v80
	v_rndne_f32_e32 v80, v80
	v_mul_f32_e32 v81, 0x2f800000, v80
	v_floor_f32_e32 v81, v81
	v_fmac_f32_e32 v80, 0xcf800000, v81
	v_cvt_u32_f32_e32 v80, v80
	v_cvt_u32_f32_e32 v81, v81
	v_mov_b32_e32 v164, v80
	v_mov_b32_e32 v165, v81
; DI void ss_add(ssacc_t* p, float v) { atomicAdd(p, (ssacc_t)__float2ull_rn(v * 4294967296.f)); }
; DI unsigned cvtpk(float lo, float hi) { f32x2 v = {lo, hi}; bf16x2_t b = __builtin_convertvector(v, bf16x2_t); return __builtin_bit_cast(unsigned, b); }
; DI float sigmoidf_(float x) { return __builtin_amdgcn_rcpf(1.f + fexp2(-LOG2E * x)); }
; DI float quad_sum(float s) { s += __shfl_xor(s, 16); s += __shfl_xor(s, 32); return s; }
;     DI bf16_t* YCAT() const { return (bf16_t*)(ws + WS_YCAT); }
;     DI void operator()(const Acc& acc, const Unit& u, int wr, int wc, int fr, int fq) const {
; #pragma unroll
;         for (int ai = 0; ai < 2; ++ai)
; #pragma unroll
;             for (int m = 0; m < 4; ++m) {
;                 asm volatile("" ::: "memory");
;                 const int row = u.pm * 256 + ai * 128 + wr * 64 + m * 16 + fr;
;                 float sq = 0.f;
; #pragma unroll
;                 for (int bj = 0; bj < 2; ++bj) {
;                     const f32x4 v0 = acc[ai][bj][m][0], v1 = acc[ai][bj][m][1];
;                     const int i0 = (u.pn * 256 + bj * 128 + wc * 32 + 8 * fq) >> 1;
;                     const f32x4 b1 = *(const f32x4*)(bglu + i0), b2 = *(const f32x4*)(bglu + 512 + i0);
;                     const float o0 = (v0[0] + b1[0]) * sigmoidf_(v0[1] + b2[0]), o1 = (v0[2] + b1[1]) * sigmoidf_(v0[3] + b2[1]);
;                     const float o2 = (v1[0] + b1[2]) * sigmoidf_(v1[1] + b2[2]), o3 = (v1[2] + b1[3]) * sigmoidf_(v1[3] + b2[3]);
;                     sq += (o0 * o0 + o1 * o1) + (o2 * o2 + o3 * o3);
;                     u32x2 w; w.x = cvtpk(o0, o1); w.y = cvtpk(o2, o3);
;                     *(u32x2*)(YCAT + (size_t)row * 2048 + i0) = w;
;                 }
;                 sq = quad_sum(sq); if (fq == 0) ss_add(ss + row, sq);
;             }
;     }
.LBB0_1178:
	s_or_b64 exec, exec, s[14:15]
	s_waitcnt lgkmcnt(0)
	v_or_b32_e32 v88, 48, v144
	v_ashrrev_i32_e32 v89, 31, v88
	v_lshlrev_b64 v[88:89], 12, v[88:89]
	v_lshl_add_u64 v[88:89], s[52:53], 0, v[88:89]
	v_lshl_add_u64 v[88:89], v[142:143], 1, v[88:89]
	v_mov_b32_e32 v80, v208
	v_mov_b32_e32 v81, v209
	v_mov_b32_e32 v82, v210
	v_mov_b32_e32 v83, v211
	v_mov_b32_e32 v84, v212
	v_mov_b32_e32 v85, v213
	v_mov_b32_e32 v86, v214
	v_mov_b32_e32 v87, v215
	v_add_f32_e32 v80, v77, v80
	v_add_f32_e32 v79, v79, v81
	v_mov_b32_e32 v77, v78
	v_add_f32_e32 v78, v73, v82
	v_add_f32_e32 v75, v75, v83
	v_mov_b32_e32 v73, v74
	v_mul_f32_e32 v74, 0xbfb8aa3b, v80
	v_mul_f32_e32 v79, 0xbfb8aa3b, v79
	v_mul_f32_e32 v78, 0xbfb8aa3b, v78
	v_mul_f32_e32 v75, 0xbfb8aa3b, v75
	v_exp_f32_e32 v74, v74
	v_exp_f32_e32 v79, v79
	v_exp_f32_e32 v78, v78
	v_exp_f32_e32 v75, v75
	v_add_f32_e32 v74, 1.0, v74
	v_add_f32_e32 v79, 1.0, v79
	v_add_f32_e32 v78, 1.0, v78
	v_add_f32_e32 v80, 1.0, v75
	v_rcp_f32_e32 v74, v74
	v_rcp_f32_e32 v75, v79
	v_rcp_f32_e32 v78, v78
	v_rcp_f32_e32 v79, v80
	v_pk_add_f32 v[76:77], v[76:77], v[84:85]
	v_pk_add_f32 v[72:73], v[72:73], v[86:87]
	v_pk_mul_f32 v[80:81], v[76:77], v[74:75]
	v_pk_mul_f32 v[82:83], v[72:73], v[78:79]
	v_cvt_pk_bf16_f32 v72, v80, v81
	v_cvt_pk_bf16_f32 v73, v82, v83
	global_store_dwordx2 v[88:89], v[72:73], off
	s_nop 0
	v_pk_mul_f32 v[80:81], v[80:81], v[80:81]
	v_pk_mul_f32 v[82:83], v[82:83], v[82:83]
	v_add_f32_e32 v80, v80, v81
	v_add_f32_e32 v82, v82, v83
	v_add_f32_e32 v80, v80, v82
	v_mov_b32_e32 v72, v216
	v_mov_b32_e32 v73, v217
	v_mov_b32_e32 v74, v218
	v_mov_b32_e32 v75, v219
	v_mov_b32_e32 v76, v220
	v_mov_b32_e32 v77, v221
	v_mov_b32_e32 v78, v222
	v_mov_b32_e32 v79, v223
	v_add_f32_e32 v72, v69, v72
	v_add_f32_e32 v71, v71, v73
	v_mov_b32_e32 v69, v70
	v_add_f32_e32 v70, v65, v74
	v_add_f32_e32 v67, v67, v75
	v_mov_b32_e32 v65, v66
	v_mul_f32_e32 v66, 0xbfb8aa3b, v72
	v_mul_f32_e32 v71, 0xbfb8aa3b, v71
	v_mul_f32_e32 v70, 0xbfb8aa3b, v70
	v_mul_f32_e32 v67, 0xbfb8aa3b, v67
	v_exp_f32_e32 v66, v66
	v_exp_f32_e32 v71, v71
	v_exp_f32_e32 v70, v70
	v_exp_f32_e32 v67, v67
	v_add_f32_e32 v66, 1.0, v66
	v_add_f32_e32 v71, 1.0, v71
	v_add_f32_e32 v70, 1.0, v70
	v_add_f32_e32 v72, 1.0, v67
	v_rcp_f32_e32 v66, v66
	v_rcp_f32_e32 v67, v71
	v_rcp_f32_e32 v70, v70
	v_rcp_f32_e32 v71, v72
	v_pk_add_f32 v[68:69], v[68:69], v[76:77]
	v_pk_add_f32 v[64:65], v[64:65], v[78:79]
	v_pk_mul_f32 v[66:67], v[68:69], v[66:67]
	v_pk_mul_f32 v[68:69], v[64:65], v[70:71]
	v_pk_mul_f32 v[64:65], v[66:67], v[66:67]
	v_pk_mul_f32 v[70:71], v[68:69], v[68:69]
	v_add_f32_e32 v64, v64, v65
	v_add_f32_e32 v70, v70, v71
	v_add_f32_e32 v64, v64, v70
	v_add_f32_e32 v64, v80, v64
	ds_bpermute_b32 v65, v120, v64
	v_cvt_pk_bf16_f32 v66, v66, v67
	v_cvt_pk_bf16_f32 v67, v68, v69
	global_store_dwordx2 v[88:89], v[66:67], off offset:128
	s_waitcnt lgkmcnt(0)
	v_add_f32_e32 v64, v64, v65
	ds_bpermute_b32 v65, v114, v64
	s_and_saveexec_b64 s[14:15], s[48:49]
	s_cbranch_execz .LBB0_1180
	s_waitcnt lgkmcnt(0)
	v_add_f32_e32 v64, v64, v65
	v_mul_f32_e32 v64, 0x4f800000, v64
	v_rndne_f32_e32 v64, v64
	v_mul_f32_e32 v65, 0x2f800000, v64
	v_floor_f32_e32 v65, v65
	v_fmac_f32_e32 v64, 0xcf800000, v65
	v_cvt_u32_f32_e32 v64, v64
	v_cvt_u32_f32_e32 v65, v65
	v_mov_b32_e32 v166, v64
	v_mov_b32_e32 v167, v65
.LBB0_1180:
	s_or_b64 exec, exec, s[14:15]
	s_waitcnt lgkmcnt(0)
	v_add_u32_e32 v72, 0x80, v144
	v_ashrrev_i32_e32 v73, 31, v72
	v_lshlrev_b64 v[72:73], 12, v[72:73]
	v_lshl_add_u64 v[72:73], s[52:53], 0, v[72:73]
	v_lshl_add_u64 v[72:73], v[142:143], 1, v[72:73]
	v_mov_b32_e32 v64, v208
	v_mov_b32_e32 v65, v209
	v_mov_b32_e32 v66, v210
	v_mov_b32_e32 v67, v211
	v_mov_b32_e32 v68, v212
	v_mov_b32_e32 v69, v213
	v_mov_b32_e32 v70, v214
	v_mov_b32_e32 v71, v215
	v_add_f32_e32 v64, v61, v64
	v_add_f32_e32 v63, v63, v65
	v_mov_b32_e32 v61, v62
	v_add_f32_e32 v62, v57, v66
	v_add_f32_e32 v59, v59, v67
	v_mov_b32_e32 v57, v58
	v_mul_f32_e32 v58, 0xbfb8aa3b, v64
	v_mul_f32_e32 v63, 0xbfb8aa3b, v63
	v_mul_f32_e32 v62, 0xbfb8aa3b, v62
	v_mul_f32_e32 v59, 0xbfb8aa3b, v59
	v_exp_f32_e32 v58, v58
	v_exp_f32_e32 v63, v63
	v_exp_f32_e32 v62, v62
	v_exp_f32_e32 v59, v59
	v_add_f32_e32 v58, 1.0, v58
	v_add_f32_e32 v63, 1.0, v63
	v_add_f32_e32 v62, 1.0, v62
	v_add_f32_e32 v64, 1.0, v59
	v_rcp_f32_e32 v58, v58
	v_rcp_f32_e32 v59, v63
	v_rcp_f32_e32 v62, v62
	v_rcp_f32_e32 v63, v64
	v_pk_add_f32 v[60:61], v[60:61], v[68:69]
	v_pk_add_f32 v[56:57], v[56:57], v[70:71]
	v_pk_mul_f32 v[64:65], v[60:61], v[58:59]
	v_pk_mul_f32 v[66:67], v[56:57], v[62:63]
	v_cvt_pk_bf16_f32 v56, v64, v65
	v_cvt_pk_bf16_f32 v57, v66, v67
	global_store_dwordx2 v[72:73], v[56:57], off
	s_nop 0
	v_pk_mul_f32 v[64:65], v[64:65], v[64:65]
	v_pk_mul_f32 v[66:67], v[66:67], v[66:67]
	v_add_f32_e32 v64, v64, v65
	v_add_f32_e32 v66, v66, v67
	v_add_f32_e32 v64, v64, v66
	v_mov_b32_e32 v56, v216
	v_mov_b32_e32 v57, v217
	v_mov_b32_e32 v58, v218
	v_mov_b32_e32 v59, v219
	v_mov_b32_e32 v60, v220
	v_mov_b32_e32 v61, v221
	v_mov_b32_e32 v62, v222
	v_mov_b32_e32 v63, v223
	v_add_f32_e32 v56, v53, v56
	v_add_f32_e32 v55, v55, v57
	v_mov_b32_e32 v53, v54
	v_add_f32_e32 v54, v49, v58
	v_add_f32_e32 v51, v51, v59
	v_mov_b32_e32 v49, v50
	v_mul_f32_e32 v50, 0xbfb8aa3b, v56
	v_mul_f32_e32 v55, 0xbfb8aa3b, v55
	v_mul_f32_e32 v54, 0xbfb8aa3b, v54
	v_mul_f32_e32 v51, 0xbfb8aa3b, v51
	v_exp_f32_e32 v50, v50
	v_exp_f32_e32 v55, v55
	v_exp_f32_e32 v54, v54
	v_exp_f32_e32 v51, v51
	v_add_f32_e32 v50, 1.0, v50
	v_add_f32_e32 v55, 1.0, v55
	v_add_f32_e32 v54, 1.0, v54
	v_add_f32_e32 v56, 1.0, v51
	v_rcp_f32_e32 v50, v50
	v_rcp_f32_e32 v51, v55
	v_rcp_f32_e32 v54, v54
	v_rcp_f32_e32 v55, v56
	v_pk_add_f32 v[52:53], v[52:53], v[60:61]
	v_pk_add_f32 v[48:49], v[48:49], v[62:63]
	v_pk_mul_f32 v[50:51], v[52:53], v[50:51]
	v_pk_mul_f32 v[52:53], v[48:49], v[54:55]
	v_pk_mul_f32 v[48:49], v[50:51], v[50:51]
	v_pk_mul_f32 v[54:55], v[52:53], v[52:53]
	v_add_f32_e32 v48, v48, v49
	v_add_f32_e32 v54, v54, v55
	v_add_f32_e32 v48, v48, v54
	v_add_f32_e32 v48, v64, v48
	ds_bpermute_b32 v49, v120, v48
	v_cvt_pk_bf16_f32 v50, v50, v51
	v_cvt_pk_bf16_f32 v51, v52, v53
	global_store_dwordx2 v[72:73], v[50:51], off offset:128
	s_waitcnt lgkmcnt(0)
	v_add_f32_e32 v48, v48, v49
	ds_bpermute_b32 v49, v114, v48
	s_and_saveexec_b64 s[14:15], s[48:49]
	s_cbranch_execz .LBB0_1182
	s_waitcnt lgkmcnt(0)
	v_add_f32_e32 v48, v48, v49
	v_mul_f32_e32 v48, 0x4f800000, v48
	v_rndne_f32_e32 v48, v48
	v_mul_f32_e32 v49, 0x2f800000, v48
	v_floor_f32_e32 v49, v49
	v_fmac_f32_e32 v48, 0xcf800000, v49
	v_cvt_u32_f32_e32 v48, v48
	v_cvt_u32_f32_e32 v49, v49
	v_mov_b32_e32 v168, v48
	v_mov_b32_e32 v169, v49
; DI void ss_add(ssacc_t* p, float v) { atomicAdd(p, (ssacc_t)__float2ull_rn(v * 4294967296.f)); }
; DI unsigned cvtpk(float lo, float hi) { f32x2 v = {lo, hi}; bf16x2_t b = __builtin_convertvector(v, bf16x2_t); return __builtin_bit_cast(unsigned, b); }
; DI float sigmoidf_(float x) { return __builtin_amdgcn_rcpf(1.f + fexp2(-LOG2E * x)); }
; DI float quad_sum(float s) { s += __shfl_xor(s, 16); s += __shfl_xor(s, 32); return s; }
;     DI bf16_t* YCAT() const { return (bf16_t*)(ws + WS_YCAT); }
;     DI void operator()(const Acc& acc, const Unit& u, int wr, int wc, int fr, int fq) const {
; #pragma unroll
;         for (int ai = 0; ai < 2; ++ai)
; #pragma unroll
;             for (int m = 0; m < 4; ++m) {
;                 asm volatile("" ::: "memory");
;                 const int row = u.pm * 256 + ai * 128 + wr * 64 + m * 16 + fr;
;                 float sq = 0.f;
; #pragma unroll
;                 for (int bj = 0; bj < 2; ++bj) {
;                     const f32x4 v0 = acc[ai][bj][m][0], v1 = acc[ai][bj][m][1];
;                     const int i0 = (u.pn * 256 + bj * 128 + wc * 32 + 8 * fq) >> 1;
;                     const f32x4 b1 = *(const f32x4*)(bglu + i0), b2 = *(const f32x4*)(bglu + 512 + i0);
;                     const float o0 = (v0[0] + b1[0]) * sigmoidf_(v0[1] + b2[0]), o1 = (v0[2] + b1[1]) * sigmoidf_(v0[3] + b2[1]);
;                     const float o2 = (v1[0] + b1[2]) * sigmoidf_(v1[1] + b2[2]), o3 = (v1[2] + b1[3]) * sigmoidf_(v1[3] + b2[3]);
;                     sq += (o0 * o0 + o1 * o1) + (o2 * o2 + o3 * o3);
;                     u32x2 w; w.x = cvtpk(o0, o1); w.y = cvtpk(o2, o3);
;                     *(u32x2*)(YCAT + (size_t)row * 2048 + i0) = w;
;                 }
;                 sq = quad_sum(sq); if (fq == 0) ss_add(ss + row, sq);
;             }
;     }
.LBB0_1182:
	s_or_b64 exec, exec, s[14:15]
	s_waitcnt lgkmcnt(0)
	v_add_u32_e32 v56, 0x90, v144
	v_ashrrev_i32_e32 v57, 31, v56
	v_lshlrev_b64 v[56:57], 12, v[56:57]
	v_lshl_add_u64 v[56:57], s[52:53], 0, v[56:57]
	v_lshl_add_u64 v[56:57], v[142:143], 1, v[56:57]
	v_mov_b32_e32 v48, v208
	v_mov_b32_e32 v49, v209
	v_mov_b32_e32 v50, v210
	v_mov_b32_e32 v51, v211
	v_mov_b32_e32 v52, v212
	v_mov_b32_e32 v53, v213
	v_mov_b32_e32 v54, v214
	v_mov_b32_e32 v55, v215
	v_add_f32_e32 v48, v45, v48
	v_add_f32_e32 v47, v47, v49
	v_mov_b32_e32 v45, v46
	v_add_f32_e32 v46, v41, v50
	v_add_f32_e32 v43, v43, v51
	v_mov_b32_e32 v41, v42
	v_mul_f32_e32 v42, 0xbfb8aa3b, v48
	v_mul_f32_e32 v47, 0xbfb8aa3b, v47
	v_mul_f32_e32 v46, 0xbfb8aa3b, v46
	v_mul_f32_e32 v43, 0xbfb8aa3b, v43
	v_exp_f32_e32 v42, v42
	v_exp_f32_e32 v47, v47
	v_exp_f32_e32 v46, v46
	v_exp_f32_e32 v43, v43
	v_add_f32_e32 v42, 1.0, v42
	v_add_f32_e32 v47, 1.0, v47
	v_add_f32_e32 v46, 1.0, v46
	v_add_f32_e32 v48, 1.0, v43
	v_rcp_f32_e32 v42, v42
	v_rcp_f32_e32 v43, v47
	v_rcp_f32_e32 v46, v46
	v_rcp_f32_e32 v47, v48
	v_pk_add_f32 v[44:45], v[44:45], v[52:53]
	v_pk_add_f32 v[40:41], v[40:41], v[54:55]
	v_pk_mul_f32 v[48:49], v[44:45], v[42:43]
	v_pk_mul_f32 v[50:51], v[40:41], v[46:47]
	v_cvt_pk_bf16_f32 v40, v48, v49
	v_cvt_pk_bf16_f32 v41, v50, v51
	global_store_dwordx2 v[56:57], v[40:41], off
	s_nop 0
	v_pk_mul_f32 v[48:49], v[48:49], v[48:49]
	v_pk_mul_f32 v[50:51], v[50:51], v[50:51]
	v_add_f32_e32 v48, v48, v49
	v_add_f32_e32 v50, v50, v51
	v_add_f32_e32 v48, v48, v50
	v_mov_b32_e32 v40, v216
	v_mov_b32_e32 v41, v217
	v_mov_b32_e32 v42, v218
	v_mov_b32_e32 v43, v219
	v_mov_b32_e32 v44, v220
	v_mov_b32_e32 v45, v221
	v_mov_b32_e32 v46, v222
	v_mov_b32_e32 v47, v223
	v_add_f32_e32 v40, v37, v40
	v_add_f32_e32 v39, v39, v41
	v_mov_b32_e32 v37, v38
	v_add_f32_e32 v38, v33, v42
	v_add_f32_e32 v35, v35, v43
	v_mov_b32_e32 v33, v34
	v_mul_f32_e32 v34, 0xbfb8aa3b, v40
	v_mul_f32_e32 v39, 0xbfb8aa3b, v39
	v_mul_f32_e32 v38, 0xbfb8aa3b, v38
	v_mul_f32_e32 v35, 0xbfb8aa3b, v35
	v_exp_f32_e32 v34, v34
	v_exp_f32_e32 v39, v39
	v_exp_f32_e32 v38, v38
	v_exp_f32_e32 v35, v35
	v_add_f32_e32 v34, 1.0, v34
	v_add_f32_e32 v39, 1.0, v39
	v_add_f32_e32 v38, 1.0, v38
	v_add_f32_e32 v40, 1.0, v35
	v_rcp_f32_e32 v34, v34
	v_rcp_f32_e32 v35, v39
	v_rcp_f32_e32 v38, v38
	v_rcp_f32_e32 v39, v40
	v_pk_add_f32 v[36:37], v[36:37], v[44:45]
	v_pk_add_f32 v[32:33], v[32:33], v[46:47]
	v_pk_mul_f32 v[34:35], v[36:37], v[34:35]
	v_pk_mul_f32 v[36:37], v[32:33], v[38:39]
	v_pk_mul_f32 v[32:33], v[34:35], v[34:35]
	v_pk_mul_f32 v[38:39], v[36:37], v[36:37]
	v_add_f32_e32 v32, v32, v33
	v_add_f32_e32 v38, v38, v39
	v_add_f32_e32 v32, v32, v38
	v_add_f32_e32 v32, v48, v32
	ds_bpermute_b32 v33, v120, v32
	v_cvt_pk_bf16_f32 v34, v34, v35
	v_cvt_pk_bf16_f32 v35, v36, v37
	global_store_dwordx2 v[56:57], v[34:35], off offset:128
	s_waitcnt lgkmcnt(0)
	v_add_f32_e32 v32, v32, v33
	ds_bpermute_b32 v33, v114, v32
	s_and_saveexec_b64 s[14:15], s[48:49]
	s_cbranch_execz .LBB0_1184
	s_waitcnt lgkmcnt(0)
	v_add_f32_e32 v32, v32, v33
	v_mul_f32_e32 v32, 0x4f800000, v32
	v_rndne_f32_e32 v32, v32
	v_mul_f32_e32 v33, 0x2f800000, v32
	v_floor_f32_e32 v33, v33
	v_fmac_f32_e32 v32, 0xcf800000, v33
	v_cvt_u32_f32_e32 v32, v32
	v_cvt_u32_f32_e32 v33, v33
	v_mov_b32_e32 v170, v32
	v_mov_b32_e32 v171, v33
.LBB0_1184:
	s_or_b64 exec, exec, s[14:15]
	s_waitcnt lgkmcnt(0)
	v_add_u32_e32 v40, 0xa0, v144
	v_ashrrev_i32_e32 v41, 31, v40
	v_lshlrev_b64 v[40:41], 12, v[40:41]
	v_lshl_add_u64 v[40:41], s[52:53], 0, v[40:41]
	v_lshl_add_u64 v[40:41], v[142:143], 1, v[40:41]
	v_mov_b32_e32 v32, v208
	v_mov_b32_e32 v33, v209
	v_mov_b32_e32 v34, v210
	v_mov_b32_e32 v35, v211
	v_mov_b32_e32 v36, v212
	v_mov_b32_e32 v37, v213
	v_mov_b32_e32 v38, v214
	v_mov_b32_e32 v39, v215
	v_add_f32_e32 v32, v29, v32
	v_add_f32_e32 v31, v31, v33
	v_mov_b32_e32 v29, v30
	v_add_f32_e32 v30, v25, v34
	v_add_f32_e32 v27, v27, v35
	v_mov_b32_e32 v25, v26
	v_mul_f32_e32 v26, 0xbfb8aa3b, v32
	v_mul_f32_e32 v31, 0xbfb8aa3b, v31
	v_mul_f32_e32 v30, 0xbfb8aa3b, v30
	v_mul_f32_e32 v27, 0xbfb8aa3b, v27
	v_exp_f32_e32 v26, v26
	v_exp_f32_e32 v31, v31
	v_exp_f32_e32 v30, v30
	v_exp_f32_e32 v27, v27
	v_add_f32_e32 v26, 1.0, v26
	v_add_f32_e32 v31, 1.0, v31
	v_add_f32_e32 v30, 1.0, v30
	v_add_f32_e32 v32, 1.0, v27
	v_rcp_f32_e32 v26, v26
	v_rcp_f32_e32 v27, v31
	v_rcp_f32_e32 v30, v30
	v_rcp_f32_e32 v31, v32
	v_pk_add_f32 v[28:29], v[28:29], v[36:37]
	v_pk_add_f32 v[24:25], v[24:25], v[38:39]
	v_pk_mul_f32 v[32:33], v[28:29], v[26:27]
	v_pk_mul_f32 v[34:35], v[24:25], v[30:31]
	v_cvt_pk_bf16_f32 v24, v32, v33
	v_cvt_pk_bf16_f32 v25, v34, v35
	global_store_dwordx2 v[40:41], v[24:25], off
	s_nop 0
	v_pk_mul_f32 v[32:33], v[32:33], v[32:33]
	v_pk_mul_f32 v[34:35], v[34:35], v[34:35]
	v_add_f32_e32 v32, v32, v33
	v_add_f32_e32 v34, v34, v35
	v_add_f32_e32 v32, v32, v34
	v_mov_b32_e32 v24, v216
	v_mov_b32_e32 v25, v217
	v_mov_b32_e32 v26, v218
	v_mov_b32_e32 v27, v219
	v_mov_b32_e32 v28, v220
	v_mov_b32_e32 v29, v221
	v_mov_b32_e32 v30, v222
	v_mov_b32_e32 v31, v223
	v_add_f32_e32 v24, v21, v24
	v_add_f32_e32 v23, v23, v25
	v_mov_b32_e32 v21, v22
	v_add_f32_e32 v22, v17, v26
	v_add_f32_e32 v19, v19, v27
	v_mov_b32_e32 v17, v18
	v_mul_f32_e32 v18, 0xbfb8aa3b, v24
	v_mul_f32_e32 v23, 0xbfb8aa3b, v23
	v_mul_f32_e32 v22, 0xbfb8aa3b, v22
	v_mul_f32_e32 v19, 0xbfb8aa3b, v19
	v_exp_f32_e32 v18, v18
	v_exp_f32_e32 v23, v23
	v_exp_f32_e32 v22, v22
	v_exp_f32_e32 v19, v19
	v_add_f32_e32 v18, 1.0, v18
	v_add_f32_e32 v23, 1.0, v23
	v_add_f32_e32 v22, 1.0, v22
	v_add_f32_e32 v24, 1.0, v19
	v_rcp_f32_e32 v18, v18
	v_rcp_f32_e32 v19, v23
	v_rcp_f32_e32 v22, v22
	v_rcp_f32_e32 v23, v24
	v_pk_add_f32 v[20:21], v[20:21], v[28:29]
	v_pk_add_f32 v[16:17], v[16:17], v[30:31]
	v_pk_mul_f32 v[18:19], v[20:21], v[18:19]
	v_pk_mul_f32 v[20:21], v[16:17], v[22:23]
	v_pk_mul_f32 v[16:17], v[18:19], v[18:19]
	v_pk_mul_f32 v[22:23], v[20:21], v[20:21]
	v_add_f32_e32 v16, v16, v17
	v_add_f32_e32 v22, v22, v23
	v_add_f32_e32 v16, v16, v22
	v_add_f32_e32 v16, v32, v16
	ds_bpermute_b32 v17, v120, v16
	v_cvt_pk_bf16_f32 v18, v18, v19
	v_cvt_pk_bf16_f32 v19, v20, v21
	global_store_dwordx2 v[40:41], v[18:19], off offset:128
	s_waitcnt lgkmcnt(0)
	v_add_f32_e32 v16, v16, v17
	ds_bpermute_b32 v17, v114, v16
	s_and_saveexec_b64 s[14:15], s[48:49]
	s_cbranch_execz .LBB0_1186
	s_waitcnt lgkmcnt(0)
	v_add_f32_e32 v16, v16, v17
	v_mul_f32_e32 v16, 0x4f800000, v16
	v_rndne_f32_e32 v16, v16
	v_mul_f32_e32 v17, 0x2f800000, v16
	v_floor_f32_e32 v17, v17
	v_fmac_f32_e32 v16, 0xcf800000, v17
	v_cvt_u32_f32_e32 v16, v16
	v_cvt_u32_f32_e32 v17, v17
	v_mov_b32_e32 v172, v16
	v_mov_b32_e32 v173, v17
; DI void ss_add(ssacc_t* p, float v) { atomicAdd(p, (ssacc_t)__float2ull_rn(v * 4294967296.f)); }
; DI unsigned cvtpk(float lo, float hi) { f32x2 v = {lo, hi}; bf16x2_t b = __builtin_convertvector(v, bf16x2_t); return __builtin_bit_cast(unsigned, b); }
; DI float sigmoidf_(float x) { return __builtin_amdgcn_rcpf(1.f + fexp2(-LOG2E * x)); }
; DI float quad_sum(float s) { s += __shfl_xor(s, 16); s += __shfl_xor(s, 32); return s; }
;     DI bf16_t* YCAT() const { return (bf16_t*)(ws + WS_YCAT); }
;     DI void operator()(const Acc& acc, const Unit& u, int wr, int wc, int fr, int fq) const {
; #pragma unroll
;         for (int ai = 0; ai < 2; ++ai)
; #pragma unroll
;             for (int m = 0; m < 4; ++m) {
;                 asm volatile("" ::: "memory");
;                 const int row = u.pm * 256 + ai * 128 + wr * 64 + m * 16 + fr;
;                 float sq = 0.f;
; #pragma unroll
;                 for (int bj = 0; bj < 2; ++bj) {
;                     const f32x4 v0 = acc[ai][bj][m][0], v1 = acc[ai][bj][m][1];
;                     const int i0 = (u.pn * 256 + bj * 128 + wc * 32 + 8 * fq) >> 1;
;                     const f32x4 b1 = *(const f32x4*)(bglu + i0), b2 = *(const f32x4*)(bglu + 512 + i0);
;                     const float o0 = (v0[0] + b1[0]) * sigmoidf_(v0[1] + b2[0]), o1 = (v0[2] + b1[1]) * sigmoidf_(v0[3] + b2[1]);
;                     const float o2 = (v1[0] + b1[2]) * sigmoidf_(v1[1] + b2[2]), o3 = (v1[2] + b1[3]) * sigmoidf_(v1[3] + b2[3]);
;                     sq += (o0 * o0 + o1 * o1) + (o2 * o2 + o3 * o3);
;                     u32x2 w; w.x = cvtpk(o0, o1); w.y = cvtpk(o2, o3);
;                     *(u32x2*)(YCAT + (size_t)row * 2048 + i0) = w;
;                 }
;                 sq = quad_sum(sq); if (fq == 0) ss_add(ss + row, sq);
;             }
;     }
.LBB0_1186:
	s_or_b64 exec, exec, s[14:15]
	s_waitcnt lgkmcnt(0)
	v_add_u32_e32 v24, 0xb0, v144
	v_ashrrev_i32_e32 v25, 31, v24
	v_lshlrev_b64 v[24:25], 12, v[24:25]
	v_lshl_add_u64 v[24:25], s[52:53], 0, v[24:25]
	v_lshl_add_u64 v[24:25], v[142:143], 1, v[24:25]
	v_mov_b32_e32 v16, v208
	v_mov_b32_e32 v17, v209
	v_mov_b32_e32 v18, v210
	v_mov_b32_e32 v19, v211
	v_mov_b32_e32 v20, v212
	v_mov_b32_e32 v21, v213
	v_mov_b32_e32 v22, v214
	v_mov_b32_e32 v23, v215
	v_add_f32_e32 v16, v13, v16
	v_add_f32_e32 v15, v15, v17
	v_mov_b32_e32 v13, v14
	v_add_f32_e32 v14, v9, v18
	v_add_f32_e32 v11, v11, v19
	v_mov_b32_e32 v9, v10
	v_mul_f32_e32 v10, 0xbfb8aa3b, v16
	v_mul_f32_e32 v15, 0xbfb8aa3b, v15
	v_mul_f32_e32 v14, 0xbfb8aa3b, v14
	v_mul_f32_e32 v11, 0xbfb8aa3b, v11
	v_exp_f32_e32 v10, v10
	v_exp_f32_e32 v15, v15
	v_exp_f32_e32 v14, v14
	v_exp_f32_e32 v11, v11
	v_add_f32_e32 v10, 1.0, v10
	v_add_f32_e32 v15, 1.0, v15
	v_add_f32_e32 v14, 1.0, v14
	v_add_f32_e32 v16, 1.0, v11
	v_rcp_f32_e32 v10, v10
	v_rcp_f32_e32 v11, v15
	v_rcp_f32_e32 v14, v14
	v_rcp_f32_e32 v15, v16
	v_pk_add_f32 v[12:13], v[12:13], v[20:21]
	v_pk_add_f32 v[8:9], v[8:9], v[22:23]
	v_pk_mul_f32 v[16:17], v[12:13], v[10:11]
	v_pk_mul_f32 v[18:19], v[8:9], v[14:15]
	v_cvt_pk_bf16_f32 v8, v16, v17
	v_cvt_pk_bf16_f32 v9, v18, v19
	global_store_dwordx2 v[24:25], v[8:9], off
	s_nop 0
	v_pk_mul_f32 v[16:17], v[16:17], v[16:17]
	v_pk_mul_f32 v[18:19], v[18:19], v[18:19]
	v_add_f32_e32 v16, v16, v17
	v_add_f32_e32 v18, v18, v19
	v_add_f32_e32 v16, v16, v18
	v_mov_b32_e32 v8, v216
	v_mov_b32_e32 v9, v217
	v_mov_b32_e32 v10, v218
	v_mov_b32_e32 v11, v219
	v_mov_b32_e32 v12, v220
	v_mov_b32_e32 v13, v221
	v_mov_b32_e32 v14, v222
	v_mov_b32_e32 v15, v223
	v_add_f32_e32 v8, v5, v8
	v_add_f32_e32 v7, v7, v9
	v_mov_b32_e32 v5, v6
	v_add_f32_e32 v6, v1, v10
	v_add_f32_e32 v3, v3, v11
	v_mov_b32_e32 v1, v2
	v_mul_f32_e32 v2, 0xbfb8aa3b, v8
	v_mul_f32_e32 v7, 0xbfb8aa3b, v7
	v_mul_f32_e32 v6, 0xbfb8aa3b, v6
	v_mul_f32_e32 v3, 0xbfb8aa3b, v3
	v_exp_f32_e32 v2, v2
	v_exp_f32_e32 v7, v7
	v_exp_f32_e32 v6, v6
	v_exp_f32_e32 v3, v3
	v_add_f32_e32 v2, 1.0, v2
	v_add_f32_e32 v7, 1.0, v7
	v_add_f32_e32 v6, 1.0, v6
	v_add_f32_e32 v8, 1.0, v3
	v_rcp_f32_e32 v2, v2
	v_rcp_f32_e32 v3, v7
	v_rcp_f32_e32 v6, v6
	v_rcp_f32_e32 v7, v8
	v_pk_add_f32 v[4:5], v[4:5], v[12:13]
	v_pk_add_f32 v[0:1], v[0:1], v[14:15]
	v_pk_mul_f32 v[2:3], v[4:5], v[2:3]
	v_pk_mul_f32 v[4:5], v[0:1], v[6:7]
	v_pk_mul_f32 v[0:1], v[2:3], v[2:3]
	v_pk_mul_f32 v[6:7], v[4:5], v[4:5]
	v_add_f32_e32 v0, v0, v1
	v_add_f32_e32 v6, v6, v7
	v_add_f32_e32 v0, v0, v6
	v_add_f32_e32 v0, v16, v0
	ds_bpermute_b32 v1, v120, v0
	v_cvt_pk_bf16_f32 v2, v2, v3
	v_cvt_pk_bf16_f32 v3, v4, v5
	global_store_dwordx2 v[24:25], v[2:3], off offset:128
	s_waitcnt lgkmcnt(0)
	v_add_f32_e32 v0, v0, v1
	ds_bpermute_b32 v1, v114, v0
	s_and_saveexec_b64 s[14:15], s[48:49]
	s_cbranch_execz .LBB0_1188
	s_waitcnt lgkmcnt(0)
	v_add_f32_e32 v0, v0, v1
	v_mul_f32_e32 v0, 0x4f800000, v0
	v_rndne_f32_e32 v0, v0
	v_mul_f32_e32 v1, 0x2f800000, v0
	v_floor_f32_e32 v1, v1
	v_fmac_f32_e32 v0, 0xcf800000, v1
	v_cvt_u32_f32_e32 v0, v0
	v_cvt_u32_f32_e32 v1, v1
	global_atomic_add_x2 v[112:113], v[160:161], off
	global_atomic_add_x2 v[112:113], v[162:163], off offset:128
	global_atomic_add_x2 v[112:113], v[164:165], off offset:256
	global_atomic_add_x2 v[112:113], v[166:167], off offset:384
	global_atomic_add_x2 v[112:113], v[168:169], off offset:1024
	global_atomic_add_x2 v[112:113], v[170:171], off offset:1152
	global_atomic_add_x2 v[112:113], v[172:173], off offset:1280
	global_atomic_add_x2 v[112:113], v[0:1], off offset:1408
